# v56 plus lever 9 loop-edge edit: loop-carried SALU block of the five GEMM K-loops moved in front of the loop-back barrier
# baseline (speedup 1.0000x reference)
.LBB0_142:
	ds_read_b128 v[148:151], v154
	ds_read_b128 v[158:161], v154 offset:1024
	ds_read_b128 v[162:165], v154 offset:2048
	ds_read_b128 v[166:169], v154 offset:3072
	ds_read_b128 v[170:173], v155
	ds_read_b128 v[174:177], v155 offset:1024
	ds_read_b128 v[178:181], v155 offset:2048
	ds_read_b128 v[182:185], v155 offset:3072
	s_add_u32 s74, s72, 0xfffc0080
	s_addc_u32 s75, s73, -1
	s_cmp_eq_u32 s71, 12
	s_cselect_b32 s77, s1, s75
	s_cselect_b32 s76, s4, s74
	s_cselect_b32 s75, s5, s31
	s_cselect_b32 s74, s9, s29
	v_lshl_add_u64 v[220:221], s[72:73], 0, v[140:141]
	s_add_i32 m0, s13, 0xc000
	ds_read_b128 v[186:189], v156
	ds_read_b128 v[190:193], v156 offset:1024
	ds_read_b128 v[194:197], v156 offset:2048
	ds_read_b128 v[198:201], v156 offset:3072
	ds_read_b128 v[202:205], v156 offset:4096
	ds_read_b128 v[206:209], v156 offset:5120
	ds_read_b128 v[210:213], v156 offset:6144
	ds_read_b128 v[216:219], v156 offset:7168
	global_load_lds_dwordx4 v[220:221], off
	v_lshl_add_u64 v[220:221], s[72:73], 0, v[142:143]
	s_add_i32 m0, s13, 0xe000
	s_nop 0
	global_load_lds_dwordx4 v[220:221], off
	s_waitcnt vmcnt(8)
	s_waitcnt lgkmcnt(0)
	s_barrier
	s_setprio 1
	s_waitcnt lgkmcnt(0)
	v_mfma_f32_16x16x32_bf16 v[126:129], v[148:151], v[186:189], v[126:129]
	v_mfma_f32_16x16x32_bf16 v[122:125], v[162:165], v[186:189], v[122:125]
	v_mfma_f32_16x16x32_bf16 v[110:113], v[148:151], v[194:197], v[110:113]
	v_mfma_f32_16x16x32_bf16 v[106:109], v[162:165], v[194:197], v[106:109]
	v_mfma_f32_16x16x32_bf16 v[94:97], v[148:151], v[202:205], v[94:97]
	v_mfma_f32_16x16x32_bf16 v[90:93], v[162:165], v[202:205], v[90:93]
	v_mfma_f32_16x16x32_bf16 v[78:81], v[148:151], v[210:213], v[78:81]
	v_mfma_f32_16x16x32_bf16 v[74:77], v[162:165], v[210:213], v[74:77]
	v_mfma_f32_16x16x32_bf16 v[126:129], v[158:161], v[190:193], v[126:129]
	v_mfma_f32_16x16x32_bf16 v[122:125], v[166:169], v[190:193], v[122:125]
	v_mfma_f32_16x16x32_bf16 v[110:113], v[158:161], v[198:201], v[110:113]
	v_mfma_f32_16x16x32_bf16 v[106:109], v[166:169], v[198:201], v[106:109]
	v_mfma_f32_16x16x32_bf16 v[94:97], v[158:161], v[206:209], v[94:97]
	v_mfma_f32_16x16x32_bf16 v[90:93], v[166:169], v[206:209], v[90:93]
	v_mfma_f32_16x16x32_bf16 v[78:81], v[158:161], v[216:219], v[78:81]
	v_mfma_f32_16x16x32_bf16 v[74:77], v[166:169], v[216:219], v[74:77]
	s_setprio 0
	s_setprio 1
	v_mfma_f32_16x16x32_bf16 v[118:121], v[170:173], v[186:189], v[118:121]
	v_mfma_f32_16x16x32_bf16 v[114:117], v[178:181], v[186:189], v[114:117]
	v_mfma_f32_16x16x32_bf16 v[102:105], v[170:173], v[194:197], v[102:105]
	v_mfma_f32_16x16x32_bf16 v[98:101], v[178:181], v[194:197], v[98:101]
	v_mfma_f32_16x16x32_bf16 v[86:89], v[170:173], v[202:205], v[86:89]
	v_mfma_f32_16x16x32_bf16 v[82:85], v[178:181], v[202:205], v[82:85]
	v_mfma_f32_16x16x32_bf16 v[70:73], v[170:173], v[210:213], v[70:73]
	v_mfma_f32_16x16x32_bf16 v[66:69], v[178:181], v[210:213], v[66:69]
	v_mfma_f32_16x16x32_bf16 v[118:121], v[174:177], v[190:193], v[118:121]
	v_mfma_f32_16x16x32_bf16 v[114:117], v[182:185], v[190:193], v[114:117]
	v_mfma_f32_16x16x32_bf16 v[102:105], v[174:177], v[198:201], v[102:105]
	v_mfma_f32_16x16x32_bf16 v[98:101], v[182:185], v[198:201], v[98:101]
	v_mfma_f32_16x16x32_bf16 v[86:89], v[174:177], v[206:209], v[86:89]
	v_mfma_f32_16x16x32_bf16 v[82:85], v[182:185], v[206:209], v[82:85]
	v_mfma_f32_16x16x32_bf16 v[70:73], v[174:177], v[216:219], v[70:73]
	v_mfma_f32_16x16x32_bf16 v[66:69], v[182:185], v[216:219], v[66:69]
	s_setprio 0
	s_barrier
	s_add_i32 vcc_lo, s91, s3
	v_lshl_add_u64 v[220:221], s[74:75], 0, v[132:133]
	s_mov_b32 m0, vcc_lo
	ds_read_b128 v[186:189], v156 offset:16384
	ds_read_b128 v[190:193], v156 offset:17408
	ds_read_b128 v[194:197], v156 offset:18432
	ds_read_b128 v[198:201], v156 offset:19456
	ds_read_b128 v[202:205], v156 offset:20480
	ds_read_b128 v[206:209], v156 offset:21504
	ds_read_b128 v[210:213], v156 offset:22528
	ds_read_b128 v[216:219], v156 offset:23552
	global_load_lds_dwordx4 v[220:221], off
	s_add_i32 m0, vcc_lo, 0x2000
	s_add_u32 vcc_lo, s74, 0x40000
	v_lshl_add_u64 v[222:223], s[74:75], 0, v[136:137]
	s_addc_u32 vcc_hi, s75, 0
	s_add_i32 s88, s10, s3
	global_load_lds_dwordx4 v[222:223], off
	v_lshl_add_u64 v[224:225], vcc, 0, v[132:133]
	s_mov_b32 m0, s88
	v_lshl_add_u64 v[226:227], s[76:77], 0, v[134:135]
	global_load_lds_dwordx4 v[224:225], off
	v_lshl_add_u64 v[224:225], vcc, 0, v[136:137]
	s_add_i32 m0, s88, 0x2000
	s_nop 0
	global_load_lds_dwordx4 v[224:225], off
	v_lshl_add_u64 v[224:225], s[76:77], 0, v[130:131]
	s_mov_b32 m0, s13
	s_nop 0
	global_load_lds_dwordx4 v[224:225], off
	s_mov_b32 m0, s78
	s_nop 0
	global_load_lds_dwordx4 v[226:227], off
	s_waitcnt vmcnt(8)
	s_waitcnt lgkmcnt(0)
	s_barrier
	s_setprio 1
	s_waitcnt lgkmcnt(0)
	v_mfma_f32_16x16x32_bf16 v[62:65], v[148:151], v[186:189], v[62:65]
	v_mfma_f32_16x16x32_bf16 v[58:61], v[162:165], v[186:189], v[58:61]
	v_mfma_f32_16x16x32_bf16 v[46:49], v[148:151], v[194:197], v[46:49]
	v_mfma_f32_16x16x32_bf16 v[42:45], v[162:165], v[194:197], v[42:45]
	v_mfma_f32_16x16x32_bf16 v[30:33], v[148:151], v[202:205], v[30:33]
	v_mfma_f32_16x16x32_bf16 v[26:29], v[162:165], v[202:205], v[26:29]
	v_mfma_f32_16x16x32_bf16 v[14:17], v[148:151], v[210:213], v[14:17]
	v_mfma_f32_16x16x32_bf16 v[10:13], v[162:165], v[210:213], v[10:13]
	v_mfma_f32_16x16x32_bf16 v[62:65], v[158:161], v[190:193], v[62:65]
	v_mfma_f32_16x16x32_bf16 v[58:61], v[166:169], v[190:193], v[58:61]
	v_mfma_f32_16x16x32_bf16 v[46:49], v[158:161], v[198:201], v[46:49]
	v_mfma_f32_16x16x32_bf16 v[42:45], v[166:169], v[198:201], v[42:45]
	v_mfma_f32_16x16x32_bf16 v[30:33], v[158:161], v[206:209], v[30:33]
	v_mfma_f32_16x16x32_bf16 v[26:29], v[166:169], v[206:209], v[26:29]
	v_mfma_f32_16x16x32_bf16 v[14:17], v[158:161], v[216:219], v[14:17]
	v_mfma_f32_16x16x32_bf16 v[10:13], v[166:169], v[216:219], v[10:13]
	s_setprio 0
	s_setprio 1
	v_mfma_f32_16x16x32_bf16 v[54:57], v[170:173], v[186:189], v[54:57]
	v_mfma_f32_16x16x32_bf16 v[50:53], v[178:181], v[186:189], v[50:53]
	v_mfma_f32_16x16x32_bf16 v[38:41], v[170:173], v[194:197], v[38:41]
	v_mfma_f32_16x16x32_bf16 v[34:37], v[178:181], v[194:197], v[34:37]
	v_mfma_f32_16x16x32_bf16 v[22:25], v[170:173], v[202:205], v[22:25]
	v_mfma_f32_16x16x32_bf16 v[18:21], v[178:181], v[202:205], v[18:21]
	v_mfma_f32_16x16x32_bf16 v[6:9], v[170:173], v[210:213], v[6:9]
	v_mfma_f32_16x16x32_bf16 v[2:5], v[178:181], v[210:213], v[2:5]
	v_mfma_f32_16x16x32_bf16 v[54:57], v[174:177], v[190:193], v[54:57]
	v_mfma_f32_16x16x32_bf16 v[50:53], v[182:185], v[190:193], v[50:53]
	v_mfma_f32_16x16x32_bf16 v[38:41], v[174:177], v[198:201], v[38:41]
	v_mfma_f32_16x16x32_bf16 v[34:37], v[182:185], v[198:201], v[34:37]
	v_mfma_f32_16x16x32_bf16 v[22:25], v[174:177], v[206:209], v[22:25]
	v_mfma_f32_16x16x32_bf16 v[18:21], v[182:185], v[206:209], v[18:21]
	v_mfma_f32_16x16x32_bf16 v[6:9], v[174:177], v[216:219], v[6:9]
	v_mfma_f32_16x16x32_bf16 v[2:5], v[182:185], v[216:219], v[2:5]
	s_setprio 0
	s_barrier
	s_add_i32 s88, 0, 0x18000
	v_add_u32_e32 v157, s88, v152
	s_add_i32 s89, 0, 0x1c000
	ds_read_b128 v[148:151], v157
	ds_read_b128 v[158:161], v157 offset:1024
	ds_read_b128 v[162:165], v157 offset:2048
	ds_read_b128 v[166:169], v157 offset:3072
	v_add_u32_e32 v157, s89, v152
	ds_read_b128 v[170:173], v157
	ds_read_b128 v[174:177], v157 offset:1024
	ds_read_b128 v[178:181], v157 offset:2048
	ds_read_b128 v[182:185], v157 offset:3072
	s_add_u32 s76, s76, 0x40000
	s_addc_u32 s77, s77, 0
	s_mov_b32 m0, s79
	v_lshl_add_u64 v[228:229], s[76:77], 0, v[130:131]
	ds_read_b128 v[186:189], v156 offset:32768
	ds_read_b128 v[190:193], v156 offset:33792
	ds_read_b128 v[194:197], v156 offset:34816
	ds_read_b128 v[198:201], v156 offset:35840
	ds_read_b128 v[202:205], v156 offset:36864
	ds_read_b128 v[206:209], v156 offset:37888
	ds_read_b128 v[210:213], v156 offset:38912
	ds_read_b128 v[216:219], v156 offset:39936
	global_load_lds_dwordx4 v[228:229], off
	v_lshl_add_u64 v[228:229], s[76:77], 0, v[134:135]
	s_mov_b32 m0, s92
	s_nop 0
	global_load_lds_dwordx4 v[228:229], off
	s_waitcnt vmcnt(8)
	s_waitcnt lgkmcnt(0)
	s_barrier
	s_setprio 1
	s_waitcnt lgkmcnt(0)
	v_mfma_f32_16x16x32_bf16 v[126:129], v[148:151], v[186:189], v[126:129]
	v_mfma_f32_16x16x32_bf16 v[122:125], v[162:165], v[186:189], v[122:125]
	v_mfma_f32_16x16x32_bf16 v[110:113], v[148:151], v[194:197], v[110:113]
	v_mfma_f32_16x16x32_bf16 v[106:109], v[162:165], v[194:197], v[106:109]
	v_mfma_f32_16x16x32_bf16 v[94:97], v[148:151], v[202:205], v[94:97]
	v_mfma_f32_16x16x32_bf16 v[90:93], v[162:165], v[202:205], v[90:93]
	v_mfma_f32_16x16x32_bf16 v[78:81], v[148:151], v[210:213], v[78:81]
	v_mfma_f32_16x16x32_bf16 v[74:77], v[162:165], v[210:213], v[74:77]
	v_mfma_f32_16x16x32_bf16 v[126:129], v[158:161], v[190:193], v[126:129]
	v_mfma_f32_16x16x32_bf16 v[122:125], v[166:169], v[190:193], v[122:125]
	v_mfma_f32_16x16x32_bf16 v[110:113], v[158:161], v[198:201], v[110:113]
	v_mfma_f32_16x16x32_bf16 v[106:109], v[166:169], v[198:201], v[106:109]
	v_mfma_f32_16x16x32_bf16 v[94:97], v[158:161], v[206:209], v[94:97]
	v_mfma_f32_16x16x32_bf16 v[90:93], v[166:169], v[206:209], v[90:93]
	v_mfma_f32_16x16x32_bf16 v[78:81], v[158:161], v[216:219], v[78:81]
	v_mfma_f32_16x16x32_bf16 v[74:77], v[166:169], v[216:219], v[74:77]
	s_setprio 0
	s_setprio 1
	v_mfma_f32_16x16x32_bf16 v[118:121], v[170:173], v[186:189], v[118:121]
	v_mfma_f32_16x16x32_bf16 v[114:117], v[178:181], v[186:189], v[114:117]
	v_mfma_f32_16x16x32_bf16 v[102:105], v[170:173], v[194:197], v[102:105]
	v_mfma_f32_16x16x32_bf16 v[98:101], v[178:181], v[194:197], v[98:101]
	v_mfma_f32_16x16x32_bf16 v[86:89], v[170:173], v[202:205], v[86:89]
	v_mfma_f32_16x16x32_bf16 v[82:85], v[178:181], v[202:205], v[82:85]
	v_mfma_f32_16x16x32_bf16 v[70:73], v[170:173], v[210:213], v[70:73]
	v_mfma_f32_16x16x32_bf16 v[66:69], v[178:181], v[210:213], v[66:69]
	v_mfma_f32_16x16x32_bf16 v[118:121], v[174:177], v[190:193], v[118:121]
	v_mfma_f32_16x16x32_bf16 v[114:117], v[182:185], v[190:193], v[114:117]
	v_mfma_f32_16x16x32_bf16 v[102:105], v[174:177], v[198:201], v[102:105]
	v_mfma_f32_16x16x32_bf16 v[98:101], v[182:185], v[198:201], v[98:101]
	v_mfma_f32_16x16x32_bf16 v[86:89], v[174:177], v[206:209], v[86:89]
	v_mfma_f32_16x16x32_bf16 v[82:85], v[182:185], v[206:209], v[82:85]
	v_mfma_f32_16x16x32_bf16 v[70:73], v[174:177], v[216:219], v[70:73]
	v_mfma_f32_16x16x32_bf16 v[66:69], v[182:185], v[216:219], v[66:69]
	s_setprio 0
	s_barrier
	s_add_i32 s76, s88, s3
	v_lshl_add_u64 v[220:221], v[220:221], 0, s[24:25]
	s_mov_b32 m0, s76
	ds_read_b128 v[186:189], v156 offset:49152
	ds_read_b128 v[190:193], v156 offset:50176
	ds_read_b128 v[194:197], v156 offset:51200
	ds_read_b128 v[198:201], v156 offset:52224
	ds_read_b128 v[202:205], v156 offset:53248
	ds_read_b128 v[206:209], v156 offset:54272
	ds_read_b128 v[210:213], v156 offset:55296
	ds_read_b128 v[216:219], v156 offset:56320
	global_load_lds_dwordx4 v[220:221], off
	s_add_i32 m0, s76, 0x2000
	s_add_u32 s74, s74, 0x40080
	v_lshl_add_u64 v[220:221], v[222:223], 0, s[24:25]
	s_addc_u32 s75, s75, 0
	s_add_i32 s76, s89, s3
	global_load_lds_dwordx4 v[220:221], off
	v_lshl_add_u64 v[220:221], s[74:75], 0, v[132:133]
	s_mov_b32 m0, s76
	s_nop 0
	global_load_lds_dwordx4 v[220:221], off
	v_lshl_add_u64 v[220:221], s[74:75], 0, v[136:137]
	s_add_i32 m0, s76, 0x2000
	s_nop 0
	global_load_lds_dwordx4 v[220:221], off
	v_lshl_add_u64 v[220:221], v[224:225], 0, s[24:25]
	s_mov_b32 m0, s94
	s_nop 0
	global_load_lds_dwordx4 v[220:221], off
	v_lshl_add_u64 v[220:221], v[226:227], 0, s[24:25]
	s_mov_b32 m0, s95
	s_nop 0
	global_load_lds_dwordx4 v[220:221], off
	s_waitcnt vmcnt(8)
	s_waitcnt lgkmcnt(0)
	s_barrier
	s_setprio 1
	s_waitcnt lgkmcnt(0)
	v_mfma_f32_16x16x32_bf16 v[62:65], v[148:151], v[186:189], v[62:65]
	v_mfma_f32_16x16x32_bf16 v[58:61], v[162:165], v[186:189], v[58:61]
	v_mfma_f32_16x16x32_bf16 v[46:49], v[148:151], v[194:197], v[46:49]
	v_mfma_f32_16x16x32_bf16 v[42:45], v[162:165], v[194:197], v[42:45]
	v_mfma_f32_16x16x32_bf16 v[30:33], v[148:151], v[202:205], v[30:33]
	v_mfma_f32_16x16x32_bf16 v[26:29], v[162:165], v[202:205], v[26:29]
	v_mfma_f32_16x16x32_bf16 v[14:17], v[148:151], v[210:213], v[14:17]
	v_mfma_f32_16x16x32_bf16 v[10:13], v[162:165], v[210:213], v[10:13]
	v_mfma_f32_16x16x32_bf16 v[62:65], v[158:161], v[190:193], v[62:65]
	v_mfma_f32_16x16x32_bf16 v[58:61], v[166:169], v[190:193], v[58:61]
	v_mfma_f32_16x16x32_bf16 v[46:49], v[158:161], v[198:201], v[46:49]
	v_mfma_f32_16x16x32_bf16 v[42:45], v[166:169], v[198:201], v[42:45]
	v_mfma_f32_16x16x32_bf16 v[30:33], v[158:161], v[206:209], v[30:33]
	v_mfma_f32_16x16x32_bf16 v[26:29], v[166:169], v[206:209], v[26:29]
	v_mfma_f32_16x16x32_bf16 v[14:17], v[158:161], v[216:219], v[14:17]
	v_mfma_f32_16x16x32_bf16 v[10:13], v[166:169], v[216:219], v[10:13]
	s_setprio 0
	s_setprio 1
	v_mfma_f32_16x16x32_bf16 v[54:57], v[170:173], v[186:189], v[54:57]
	v_mfma_f32_16x16x32_bf16 v[50:53], v[178:181], v[186:189], v[50:53]
	v_mfma_f32_16x16x32_bf16 v[38:41], v[170:173], v[194:197], v[38:41]
	v_mfma_f32_16x16x32_bf16 v[34:37], v[178:181], v[194:197], v[34:37]
	v_mfma_f32_16x16x32_bf16 v[22:25], v[170:173], v[202:205], v[22:25]
	v_mfma_f32_16x16x32_bf16 v[18:21], v[178:181], v[202:205], v[18:21]
	v_mfma_f32_16x16x32_bf16 v[6:9], v[170:173], v[210:213], v[6:9]
	v_mfma_f32_16x16x32_bf16 v[2:5], v[178:181], v[210:213], v[2:5]
	v_mfma_f32_16x16x32_bf16 v[54:57], v[174:177], v[190:193], v[54:57]
	v_mfma_f32_16x16x32_bf16 v[50:53], v[182:185], v[190:193], v[50:53]
	v_mfma_f32_16x16x32_bf16 v[38:41], v[174:177], v[198:201], v[38:41]
	v_mfma_f32_16x16x32_bf16 v[34:37], v[182:185], v[198:201], v[34:37]
	v_mfma_f32_16x16x32_bf16 v[22:25], v[174:177], v[206:209], v[22:25]
	v_mfma_f32_16x16x32_bf16 v[18:21], v[182:185], v[206:209], v[18:21]
	v_mfma_f32_16x16x32_bf16 v[6:9], v[174:177], v[216:219], v[6:9]
	v_mfma_f32_16x16x32_bf16 v[2:5], v[182:185], v[216:219], v[2:5]
	s_setprio 0
	s_add_i32 s71, s71, 2
	s_add_u32 s72, s72, 0x100
	s_addc_u32 s73, s73, 0
	s_add_u32 s29, s29, 0x100
	s_addc_u32 s31, s31, 0
	s_cmp_gt_u32 s71, 13
	s_barrier
	s_cbranch_scc0 .LBB0_142
	s_and_b64 vcc, exec, s[26:27]
	s_cbranch_vccz .LBB0_145
	s_barrier

.LBB0_382:
	ds_read_b128 v[148:151], v79
	ds_read_b128 v[152:155], v79 offset:1024
	ds_read_b128 v[156:159], v79 offset:2048
	ds_read_b128 v[160:163], v79 offset:3072
	ds_read_b128 v[164:167], v80
	ds_read_b128 v[168:171], v80 offset:1024
	ds_read_b128 v[172:175], v80 offset:2048
	ds_read_b128 v[176:179], v80 offset:3072
	s_add_u32 s20, s16, s18
	s_addc_u32 s21, s17, s19
	s_add_u32 s20, s20, 0xd000100
	s_addc_u32 s21, s21, 0
	s_add_u32 s74, s29, s18
	s_addc_u32 s75, s30, s19
	s_cmpk_eq_i32 s18, 0x300
	s_cselect_b32 s23, s11, s21
	s_cselect_b32 s22, s10, s20
	s_cselect_b32 s21, s9, s75
	s_cselect_b32 s20, s8, s74
	s_mov_b32 m0, s34
	v_lshl_add_u64 v[212:213], v[74:75], 0, s[18:19]
	ds_read_b128 v[180:183], v81
	ds_read_b128 v[184:187], v81 offset:1024
	ds_read_b128 v[188:191], v81 offset:2048
	ds_read_b128 v[192:195], v81 offset:3072
	ds_read_b128 v[196:199], v81 offset:4096
	ds_read_b128 v[200:203], v81 offset:5120
	global_load_lds_dwordx4 v[212:213], off
	v_lshl_add_u64 v[212:213], v[76:77], 0, s[18:19]
	s_mov_b32 m0, s35
	s_nop 0
	global_load_lds_dwordx4 v[212:213], off
	s_waitcnt vmcnt(8)
	s_waitcnt lgkmcnt(0)
	s_barrier
	s_setprio 1
	s_waitcnt lgkmcnt(0)
	v_mfma_f32_16x16x32_bf16 v[142:145], v[148:151], v[180:183], v[142:145]
	v_mfma_f32_16x16x32_bf16 v[138:141], v[156:159], v[180:183], v[138:141]
	v_mfma_f32_16x16x32_bf16 v[126:129], v[148:151], v[188:191], v[126:129]
	v_mfma_f32_16x16x32_bf16 v[122:125], v[156:159], v[188:191], v[122:125]
	v_mfma_f32_16x16x32_bf16 v[110:113], v[148:151], v[196:199], v[110:113]
	v_mfma_f32_16x16x32_bf16 v[106:109], v[156:159], v[196:199], v[106:109]
	v_mfma_f32_16x16x32_bf16 v[142:145], v[152:155], v[184:187], v[142:145]
	v_mfma_f32_16x16x32_bf16 v[138:141], v[160:163], v[184:187], v[138:141]
	v_mfma_f32_16x16x32_bf16 v[126:129], v[152:155], v[192:195], v[126:129]
	v_mfma_f32_16x16x32_bf16 v[122:125], v[160:163], v[192:195], v[122:125]
	v_mfma_f32_16x16x32_bf16 v[110:113], v[152:155], v[200:203], v[110:113]
	v_mfma_f32_16x16x32_bf16 v[106:109], v[160:163], v[200:203], v[106:109]
	s_setprio 0
	s_setprio 1
	v_mfma_f32_16x16x32_bf16 v[134:137], v[164:167], v[180:183], v[134:137]
	v_mfma_f32_16x16x32_bf16 v[130:133], v[172:175], v[180:183], v[130:133]
	v_mfma_f32_16x16x32_bf16 v[118:121], v[164:167], v[188:191], v[118:121]
	v_mfma_f32_16x16x32_bf16 v[114:117], v[172:175], v[188:191], v[114:117]
	v_mfma_f32_16x16x32_bf16 v[102:105], v[164:167], v[196:199], v[102:105]
	v_mfma_f32_16x16x32_bf16 v[98:101], v[172:175], v[196:199], v[98:101]
	v_mfma_f32_16x16x32_bf16 v[134:137], v[168:171], v[184:187], v[134:137]
	v_mfma_f32_16x16x32_bf16 v[130:133], v[176:179], v[184:187], v[130:133]
	v_mfma_f32_16x16x32_bf16 v[118:121], v[168:171], v[192:195], v[118:121]
	v_mfma_f32_16x16x32_bf16 v[114:117], v[176:179], v[192:195], v[114:117]
	v_mfma_f32_16x16x32_bf16 v[102:105], v[168:171], v[200:203], v[102:105]
	v_mfma_f32_16x16x32_bf16 v[98:101], v[176:179], v[200:203], v[98:101]
	s_setprio 0
	s_barrier
	s_mov_b32 m0, s36
	v_lshl_add_u64 v[212:213], s[20:21], 0, v[62:63]
	s_add_u32 s74, s20, 0x20000
	ds_read_b128 v[180:183], v81 offset:16384
	ds_read_b128 v[184:187], v81 offset:17408
	ds_read_b128 v[188:191], v81 offset:18432
	ds_read_b128 v[192:195], v81 offset:19456
	ds_read_b128 v[196:199], v81 offset:20480
	ds_read_b128 v[200:203], v81 offset:21504
	global_load_lds_dwordx4 v[212:213], off
	v_lshl_add_u64 v[216:217], s[20:21], 0, v[58:59]
	s_mov_b32 m0, s37
	s_addc_u32 s75, s21, 0
	global_load_lds_dwordx4 v[216:217], off
	v_lshl_add_u64 v[218:219], s[74:75], 0, v[62:63]
	s_mov_b32 m0, s62
	v_lshl_add_u64 v[220:221], s[22:23], 0, v[60:61]
	global_load_lds_dwordx4 v[218:219], off
	v_lshl_add_u64 v[218:219], s[74:75], 0, v[58:59]
	s_mov_b32 m0, s63
	s_nop 0
	global_load_lds_dwordx4 v[218:219], off
	v_lshl_add_u64 v[218:219], s[22:23], 0, v[64:65]
	s_mov_b32 m0, s4
	s_nop 0
	global_load_lds_dwordx4 v[218:219], off
	s_mov_b32 m0, s5
	s_nop 0
	global_load_lds_dwordx4 v[220:221], off
	s_waitcnt vmcnt(8)
	s_waitcnt lgkmcnt(0)
	s_barrier
	s_setprio 1
	s_waitcnt lgkmcnt(0)
	v_mfma_f32_16x16x32_bf16 v[70:73], v[148:151], v[180:183], v[70:73]
	v_mfma_f32_16x16x32_bf16 v[66:69], v[156:159], v[180:183], v[66:69]
	v_mfma_f32_16x16x32_bf16 v[46:49], v[148:151], v[188:191], v[46:49]
	v_mfma_f32_16x16x32_bf16 v[42:45], v[156:159], v[188:191], v[42:45]
	v_mfma_f32_16x16x32_bf16 v[30:33], v[148:151], v[196:199], v[30:33]
	v_mfma_f32_16x16x32_bf16 v[26:29], v[156:159], v[196:199], v[26:29]
	v_mfma_f32_16x16x32_bf16 v[70:73], v[152:155], v[184:187], v[70:73]
	v_mfma_f32_16x16x32_bf16 v[66:69], v[160:163], v[184:187], v[66:69]
	v_mfma_f32_16x16x32_bf16 v[46:49], v[152:155], v[192:195], v[46:49]
	v_mfma_f32_16x16x32_bf16 v[42:45], v[160:163], v[192:195], v[42:45]
	v_mfma_f32_16x16x32_bf16 v[30:33], v[152:155], v[200:203], v[30:33]
	v_mfma_f32_16x16x32_bf16 v[26:29], v[160:163], v[200:203], v[26:29]
	s_setprio 0
	s_setprio 1
	v_mfma_f32_16x16x32_bf16 v[54:57], v[164:167], v[180:183], v[54:57]
	v_mfma_f32_16x16x32_bf16 v[50:53], v[172:175], v[180:183], v[50:53]
	v_mfma_f32_16x16x32_bf16 v[38:41], v[164:167], v[188:191], v[38:41]
	v_mfma_f32_16x16x32_bf16 v[34:37], v[172:175], v[188:191], v[34:37]
	v_mfma_f32_16x16x32_bf16 v[22:25], v[164:167], v[196:199], v[22:25]
	v_mfma_f32_16x16x32_bf16 v[18:21], v[172:175], v[196:199], v[18:21]
	v_mfma_f32_16x16x32_bf16 v[54:57], v[168:171], v[184:187], v[54:57]
	v_mfma_f32_16x16x32_bf16 v[50:53], v[176:179], v[184:187], v[50:53]
	v_mfma_f32_16x16x32_bf16 v[38:41], v[168:171], v[192:195], v[38:41]
	v_mfma_f32_16x16x32_bf16 v[34:37], v[176:179], v[192:195], v[34:37]
	v_mfma_f32_16x16x32_bf16 v[22:25], v[168:171], v[200:203], v[22:25]
	v_mfma_f32_16x16x32_bf16 v[18:21], v[176:179], v[200:203], v[18:21]
	s_setprio 0
	s_barrier
	ds_read_b128 v[148:151], v146
	ds_read_b128 v[152:155], v146 offset:1024
	ds_read_b128 v[156:159], v146 offset:2048
	ds_read_b128 v[160:163], v146 offset:3072
	ds_read_b128 v[164:167], v147
	ds_read_b128 v[168:171], v147 offset:1024
	ds_read_b128 v[172:175], v147 offset:2048
	ds_read_b128 v[176:179], v147 offset:3072
	s_add_u32 s22, s22, 0x18000
	s_addc_u32 s23, s23, 0
	s_mov_b32 m0, s24
	v_lshl_add_u64 v[222:223], s[22:23], 0, v[64:65]
	ds_read_b128 v[180:183], v81 offset:32768
	ds_read_b128 v[184:187], v81 offset:33792
	ds_read_b128 v[188:191], v81 offset:34816
	ds_read_b128 v[192:195], v81 offset:35840
	ds_read_b128 v[196:199], v81 offset:36864
	ds_read_b128 v[200:203], v81 offset:37888
	global_load_lds_dwordx4 v[222:223], off
	v_lshl_add_u64 v[222:223], s[22:23], 0, v[60:61]
	s_mov_b32 m0, s25
	s_nop 0
	global_load_lds_dwordx4 v[222:223], off
	s_waitcnt vmcnt(8)
	s_waitcnt lgkmcnt(0)
	s_barrier
	s_setprio 1
	s_waitcnt lgkmcnt(0)
	v_mfma_f32_16x16x32_bf16 v[142:145], v[148:151], v[180:183], v[142:145]
	v_mfma_f32_16x16x32_bf16 v[138:141], v[156:159], v[180:183], v[138:141]
	v_mfma_f32_16x16x32_bf16 v[126:129], v[148:151], v[188:191], v[126:129]
	v_mfma_f32_16x16x32_bf16 v[122:125], v[156:159], v[188:191], v[122:125]
	v_mfma_f32_16x16x32_bf16 v[110:113], v[148:151], v[196:199], v[110:113]
	v_mfma_f32_16x16x32_bf16 v[106:109], v[156:159], v[196:199], v[106:109]
	v_mfma_f32_16x16x32_bf16 v[142:145], v[152:155], v[184:187], v[142:145]
	v_mfma_f32_16x16x32_bf16 v[138:141], v[160:163], v[184:187], v[138:141]
	v_mfma_f32_16x16x32_bf16 v[126:129], v[152:155], v[192:195], v[126:129]
	v_mfma_f32_16x16x32_bf16 v[122:125], v[160:163], v[192:195], v[122:125]
	v_mfma_f32_16x16x32_bf16 v[110:113], v[152:155], v[200:203], v[110:113]
	v_mfma_f32_16x16x32_bf16 v[106:109], v[160:163], v[200:203], v[106:109]
	s_setprio 0
	s_setprio 1
	v_mfma_f32_16x16x32_bf16 v[134:137], v[164:167], v[180:183], v[134:137]
	v_mfma_f32_16x16x32_bf16 v[130:133], v[172:175], v[180:183], v[130:133]
	v_mfma_f32_16x16x32_bf16 v[118:121], v[164:167], v[188:191], v[118:121]
	v_mfma_f32_16x16x32_bf16 v[114:117], v[172:175], v[188:191], v[114:117]
	v_mfma_f32_16x16x32_bf16 v[102:105], v[164:167], v[196:199], v[102:105]
	v_mfma_f32_16x16x32_bf16 v[98:101], v[172:175], v[196:199], v[98:101]
	v_mfma_f32_16x16x32_bf16 v[134:137], v[168:171], v[184:187], v[134:137]
	v_mfma_f32_16x16x32_bf16 v[130:133], v[176:179], v[184:187], v[130:133]
	v_mfma_f32_16x16x32_bf16 v[118:121], v[168:171], v[192:195], v[118:121]
	v_mfma_f32_16x16x32_bf16 v[114:117], v[176:179], v[192:195], v[114:117]
	v_mfma_f32_16x16x32_bf16 v[102:105], v[168:171], v[200:203], v[102:105]
	v_mfma_f32_16x16x32_bf16 v[98:101], v[176:179], v[200:203], v[98:101]
	s_setprio 0
	s_barrier
	s_mov_b32 m0, s64
	v_lshl_add_u64 v[212:213], v[212:213], 0, s[14:15]
	s_add_u32 s20, s20, 0x20080
	ds_read_b128 v[180:183], v81 offset:49152
	ds_read_b128 v[184:187], v81 offset:50176
	ds_read_b128 v[188:191], v81 offset:51200
	ds_read_b128 v[192:195], v81 offset:52224
	ds_read_b128 v[196:199], v81 offset:53248
	ds_read_b128 v[200:203], v81 offset:54272
	global_load_lds_dwordx4 v[212:213], off
	v_lshl_add_u64 v[212:213], v[216:217], 0, s[14:15]
	s_mov_b32 m0, s65
	s_addc_u32 s21, s21, 0
	global_load_lds_dwordx4 v[212:213], off
	v_lshl_add_u64 v[212:213], s[20:21], 0, v[62:63]
	s_mov_b32 m0, s72
	s_nop 0
	global_load_lds_dwordx4 v[212:213], off
	v_lshl_add_u64 v[212:213], s[20:21], 0, v[58:59]
	s_mov_b32 m0, s73
	s_nop 0
	global_load_lds_dwordx4 v[212:213], off
	v_lshl_add_u64 v[212:213], v[218:219], 0, s[14:15]
	s_mov_b32 m0, s27
	s_nop 0
	global_load_lds_dwordx4 v[212:213], off
	v_lshl_add_u64 v[212:213], v[220:221], 0, s[14:15]
	s_mov_b32 m0, s28
	s_nop 0
	global_load_lds_dwordx4 v[212:213], off
	s_waitcnt vmcnt(8)
	s_waitcnt lgkmcnt(0)
	s_barrier
	s_setprio 1
	s_waitcnt lgkmcnt(0)
	v_mfma_f32_16x16x32_bf16 v[70:73], v[148:151], v[180:183], v[70:73]
	v_mfma_f32_16x16x32_bf16 v[66:69], v[156:159], v[180:183], v[66:69]
	v_mfma_f32_16x16x32_bf16 v[46:49], v[148:151], v[188:191], v[46:49]
	v_mfma_f32_16x16x32_bf16 v[42:45], v[156:159], v[188:191], v[42:45]
	v_mfma_f32_16x16x32_bf16 v[30:33], v[148:151], v[196:199], v[30:33]
	v_mfma_f32_16x16x32_bf16 v[26:29], v[156:159], v[196:199], v[26:29]
	v_mfma_f32_16x16x32_bf16 v[70:73], v[152:155], v[184:187], v[70:73]
	v_mfma_f32_16x16x32_bf16 v[66:69], v[160:163], v[184:187], v[66:69]
	v_mfma_f32_16x16x32_bf16 v[46:49], v[152:155], v[192:195], v[46:49]
	v_mfma_f32_16x16x32_bf16 v[42:45], v[160:163], v[192:195], v[42:45]
	v_mfma_f32_16x16x32_bf16 v[30:33], v[152:155], v[200:203], v[30:33]
	v_mfma_f32_16x16x32_bf16 v[26:29], v[160:163], v[200:203], v[26:29]
	s_setprio 0
	s_setprio 1
	v_mfma_f32_16x16x32_bf16 v[54:57], v[164:167], v[180:183], v[54:57]
	v_mfma_f32_16x16x32_bf16 v[50:53], v[172:175], v[180:183], v[50:53]
	v_mfma_f32_16x16x32_bf16 v[38:41], v[164:167], v[188:191], v[38:41]
	v_mfma_f32_16x16x32_bf16 v[34:37], v[172:175], v[188:191], v[34:37]
	v_mfma_f32_16x16x32_bf16 v[22:25], v[164:167], v[196:199], v[22:25]
	v_mfma_f32_16x16x32_bf16 v[18:21], v[172:175], v[196:199], v[18:21]
	v_mfma_f32_16x16x32_bf16 v[54:57], v[168:171], v[184:187], v[54:57]
	v_mfma_f32_16x16x32_bf16 v[50:53], v[176:179], v[184:187], v[50:53]
	v_mfma_f32_16x16x32_bf16 v[38:41], v[168:171], v[192:195], v[38:41]
	v_mfma_f32_16x16x32_bf16 v[34:37], v[176:179], v[192:195], v[34:37]
	v_mfma_f32_16x16x32_bf16 v[22:25], v[168:171], v[200:203], v[22:25]
	v_mfma_f32_16x16x32_bf16 v[18:21], v[176:179], v[200:203], v[18:21]
	s_setprio 0
	s_add_i32 s31, s31, 2
	s_add_u32 s18, s18, 0x100
	s_addc_u32 s19, s19, 0
	s_cmp_gt_u32 s31, 5
	s_barrier
	s_cbranch_scc0 .LBB0_382
	s_cmpk_lt_u32 s0, 0x100
	s_cbranch_scc0 .LBB0_385
	s_barrier

.LBB0_451:
	v_add_u32_e32 v153, s74, v151
	ds_read_b128 v[154:157], v153
	ds_read_b128 v[158:161], v153 offset:1024
	ds_read_b128 v[162:165], v153 offset:2048
	ds_read_b128 v[166:169], v153 offset:3072
	v_add_u32_e32 v153, s75, v151
	s_add_u32 s28, s10, s26
	ds_read_b128 v[170:173], v153
	ds_read_b128 v[174:177], v153 offset:1024
	ds_read_b128 v[178:181], v153 offset:2048
	ds_read_b128 v[182:185], v153 offset:3072
	s_addc_u32 s29, s11, s27
	s_add_u32 s28, s28, 0x100
	s_addc_u32 s29, s29, 0
	s_add_u32 s80, s4, s26
	s_addc_u32 s81, s5, s27
	s_cmpk_eq_i32 s26, 0x700
	s_cselect_b32 s31, s21, s29
	s_cselect_b32 s30, s77, s28
	s_cselect_b32 s29, s19, s81
	s_cselect_b32 s28, s78, s80
	v_lshl_add_u64 v[222:223], v[146:147], 0, s[26:27]
	s_add_i32 m0, s63, 0xc000
	ds_read_b128 v[186:189], v152
	ds_read_b128 v[190:193], v152 offset:1024
	ds_read_b128 v[194:197], v152 offset:2048
	ds_read_b128 v[198:201], v152 offset:3072
	ds_read_b128 v[202:205], v152 offset:4096
	ds_read_b128 v[206:209], v152 offset:5120
	ds_read_b128 v[210:213], v152 offset:6144
	ds_read_b128 v[218:221], v152 offset:7168
	global_load_lds_dwordx4 v[222:223], off
	v_lshl_add_u64 v[222:223], v[148:149], 0, s[26:27]
	s_add_i32 m0, s63, 0xe000
	s_nop 0
	global_load_lds_dwordx4 v[222:223], off
	s_waitcnt vmcnt(8)
	s_waitcnt lgkmcnt(0)
	s_barrier
	s_setprio 1
	s_waitcnt lgkmcnt(0)
	v_mfma_f32_16x16x32_bf16 v[126:129], v[154:157], v[186:189], v[126:129]
	v_mfma_f32_16x16x32_bf16 v[122:125], v[162:165], v[186:189], v[122:125]
	v_mfma_f32_16x16x32_bf16 v[118:121], v[154:157], v[194:197], v[118:121]
	v_mfma_f32_16x16x32_bf16 v[114:117], v[162:165], v[194:197], v[114:117]
	v_mfma_f32_16x16x32_bf16 v[94:97], v[154:157], v[202:205], v[94:97]
	v_mfma_f32_16x16x32_bf16 v[90:93], v[162:165], v[202:205], v[90:93]
	v_mfma_f32_16x16x32_bf16 v[78:81], v[154:157], v[210:213], v[78:81]
	v_mfma_f32_16x16x32_bf16 v[74:77], v[162:165], v[210:213], v[74:77]
	v_mfma_f32_16x16x32_bf16 v[126:129], v[158:161], v[190:193], v[126:129]
	v_mfma_f32_16x16x32_bf16 v[122:125], v[166:169], v[190:193], v[122:125]
	v_mfma_f32_16x16x32_bf16 v[118:121], v[158:161], v[198:201], v[118:121]
	v_mfma_f32_16x16x32_bf16 v[114:117], v[166:169], v[198:201], v[114:117]
	v_mfma_f32_16x16x32_bf16 v[94:97], v[158:161], v[206:209], v[94:97]
	v_mfma_f32_16x16x32_bf16 v[90:93], v[166:169], v[206:209], v[90:93]
	v_mfma_f32_16x16x32_bf16 v[78:81], v[158:161], v[218:221], v[78:81]
	v_mfma_f32_16x16x32_bf16 v[74:77], v[166:169], v[218:221], v[74:77]
	s_setprio 0
	s_setprio 1
	v_mfma_f32_16x16x32_bf16 v[110:113], v[170:173], v[186:189], v[110:113]
	v_mfma_f32_16x16x32_bf16 v[106:109], v[178:181], v[186:189], v[106:109]
	v_mfma_f32_16x16x32_bf16 v[102:105], v[170:173], v[194:197], v[102:105]
	v_mfma_f32_16x16x32_bf16 v[98:101], v[178:181], v[194:197], v[98:101]
	v_mfma_f32_16x16x32_bf16 v[86:89], v[170:173], v[202:205], v[86:89]
	v_mfma_f32_16x16x32_bf16 v[82:85], v[178:181], v[202:205], v[82:85]
	v_mfma_f32_16x16x32_bf16 v[70:73], v[170:173], v[210:213], v[70:73]
	v_mfma_f32_16x16x32_bf16 v[66:69], v[178:181], v[210:213], v[66:69]
	v_mfma_f32_16x16x32_bf16 v[110:113], v[174:177], v[190:193], v[110:113]
	v_mfma_f32_16x16x32_bf16 v[106:109], v[182:185], v[190:193], v[106:109]
	v_mfma_f32_16x16x32_bf16 v[102:105], v[174:177], v[198:201], v[102:105]
	v_mfma_f32_16x16x32_bf16 v[98:101], v[182:185], v[198:201], v[98:101]
	v_mfma_f32_16x16x32_bf16 v[86:89], v[174:177], v[206:209], v[86:89]
	v_mfma_f32_16x16x32_bf16 v[82:85], v[182:185], v[206:209], v[82:85]
	v_mfma_f32_16x16x32_bf16 v[70:73], v[174:177], v[218:221], v[70:73]
	v_mfma_f32_16x16x32_bf16 v[66:69], v[182:185], v[218:221], v[66:69]
	s_setprio 0
	s_barrier
	s_add_i32 s80, s74, s37
	v_lshl_add_u64 v[222:223], s[28:29], 0, v[134:135]
	s_mov_b32 m0, s80
	ds_read_b128 v[186:189], v152 offset:16384
	ds_read_b128 v[190:193], v152 offset:17408
	ds_read_b128 v[194:197], v152 offset:18432
	ds_read_b128 v[198:201], v152 offset:19456
	ds_read_b128 v[202:205], v152 offset:20480
	ds_read_b128 v[206:209], v152 offset:21504
	ds_read_b128 v[210:213], v152 offset:22528
	ds_read_b128 v[218:221], v152 offset:23552
	global_load_lds_dwordx4 v[222:223], off
	s_add_i32 m0, s80, 0x2000
	s_add_u32 s80, s28, 0x40000
	v_lshl_add_u64 v[224:225], s[28:29], 0, v[130:131]
	s_addc_u32 s81, s29, 0
	s_add_i32 s88, s75, s37
	global_load_lds_dwordx4 v[224:225], off
	v_lshl_add_u64 v[226:227], s[80:81], 0, v[134:135]
	s_mov_b32 m0, s88
	v_lshl_add_u64 v[228:229], s[30:31], 0, v[132:133]
	global_load_lds_dwordx4 v[226:227], off
	v_lshl_add_u64 v[226:227], s[80:81], 0, v[130:131]
	s_add_i32 m0, s88, 0x2000
	s_nop 0
	global_load_lds_dwordx4 v[226:227], off
	v_lshl_add_u64 v[226:227], s[30:31], 0, v[136:137]
	s_mov_b32 m0, s63
	s_nop 0
	global_load_lds_dwordx4 v[226:227], off
	s_mov_b32 m0, s0
	s_nop 0
	global_load_lds_dwordx4 v[228:229], off
	s_waitcnt vmcnt(8)
	s_waitcnt lgkmcnt(0)
	s_barrier
	s_setprio 1
	s_waitcnt lgkmcnt(0)
	v_mfma_f32_16x16x32_bf16 v[62:65], v[154:157], v[186:189], v[62:65]
	v_mfma_f32_16x16x32_bf16 v[58:61], v[162:165], v[186:189], v[58:61]
	v_mfma_f32_16x16x32_bf16 v[50:53], v[154:157], v[194:197], v[50:53]
	v_mfma_f32_16x16x32_bf16 v[42:45], v[162:165], v[194:197], v[42:45]
	v_mfma_f32_16x16x32_bf16 v[30:33], v[154:157], v[202:205], v[30:33]
	v_mfma_f32_16x16x32_bf16 v[26:29], v[162:165], v[202:205], v[26:29]
	v_mfma_f32_16x16x32_bf16 v[22:25], v[154:157], v[210:213], v[22:25]
	v_mfma_f32_16x16x32_bf16 v[18:21], v[162:165], v[210:213], v[18:21]
	v_mfma_f32_16x16x32_bf16 v[62:65], v[158:161], v[190:193], v[62:65]
	v_mfma_f32_16x16x32_bf16 v[58:61], v[166:169], v[190:193], v[58:61]
	v_mfma_f32_16x16x32_bf16 v[50:53], v[158:161], v[198:201], v[50:53]
	v_mfma_f32_16x16x32_bf16 v[42:45], v[166:169], v[198:201], v[42:45]
	v_mfma_f32_16x16x32_bf16 v[30:33], v[158:161], v[206:209], v[30:33]
	v_mfma_f32_16x16x32_bf16 v[26:29], v[166:169], v[206:209], v[26:29]
	v_mfma_f32_16x16x32_bf16 v[22:25], v[158:161], v[218:221], v[22:25]
	v_mfma_f32_16x16x32_bf16 v[18:21], v[166:169], v[218:221], v[18:21]
	s_setprio 0
	s_setprio 1
	v_mfma_f32_16x16x32_bf16 v[54:57], v[170:173], v[186:189], v[54:57]
	v_mfma_f32_16x16x32_bf16 v[46:49], v[178:181], v[186:189], v[46:49]
	v_mfma_f32_16x16x32_bf16 v[38:41], v[170:173], v[194:197], v[38:41]
	v_mfma_f32_16x16x32_bf16 v[34:37], v[178:181], v[194:197], v[34:37]
	v_mfma_f32_16x16x32_bf16 v[14:17], v[170:173], v[202:205], v[14:17]
	v_mfma_f32_16x16x32_bf16 v[10:13], v[178:181], v[202:205], v[10:13]
	v_mfma_f32_16x16x32_bf16 v[6:9], v[170:173], v[210:213], v[6:9]
	v_mfma_f32_16x16x32_bf16 v[2:5], v[178:181], v[210:213], v[2:5]
	v_mfma_f32_16x16x32_bf16 v[54:57], v[174:177], v[190:193], v[54:57]
	v_mfma_f32_16x16x32_bf16 v[46:49], v[182:185], v[190:193], v[46:49]
	v_mfma_f32_16x16x32_bf16 v[38:41], v[174:177], v[198:201], v[38:41]
	v_mfma_f32_16x16x32_bf16 v[34:37], v[182:185], v[198:201], v[34:37]
	v_mfma_f32_16x16x32_bf16 v[14:17], v[174:177], v[206:209], v[14:17]
	v_mfma_f32_16x16x32_bf16 v[10:13], v[182:185], v[206:209], v[10:13]
	v_mfma_f32_16x16x32_bf16 v[6:9], v[174:177], v[218:221], v[6:9]
	v_mfma_f32_16x16x32_bf16 v[2:5], v[182:185], v[218:221], v[2:5]
	s_setprio 0
	s_barrier
	s_add_i32 s80, 0, 0x18000
	v_add_u32_e32 v153, s80, v151
	s_add_i32 s81, 0, 0x1c000
	ds_read_b128 v[154:157], v153
	ds_read_b128 v[158:161], v153 offset:1024
	ds_read_b128 v[162:165], v153 offset:2048
	ds_read_b128 v[166:169], v153 offset:3072
	v_add_u32_e32 v153, s81, v151
	ds_read_b128 v[170:173], v153
	ds_read_b128 v[174:177], v153 offset:1024
	ds_read_b128 v[178:181], v153 offset:2048
	ds_read_b128 v[182:185], v153 offset:3072
	s_add_u32 s30, s30, 0x40000
	s_addc_u32 s31, s31, 0
	s_mov_b32 m0, s1
	v_lshl_add_u64 v[230:231], s[30:31], 0, v[136:137]
	ds_read_b128 v[186:189], v152 offset:32768
	ds_read_b128 v[190:193], v152 offset:33792
	ds_read_b128 v[194:197], v152 offset:34816
	ds_read_b128 v[198:201], v152 offset:35840
	ds_read_b128 v[202:205], v152 offset:36864
	ds_read_b128 v[206:209], v152 offset:37888
	ds_read_b128 v[210:213], v152 offset:38912
	ds_read_b128 v[218:221], v152 offset:39936
	global_load_lds_dwordx4 v[230:231], off
	v_lshl_add_u64 v[230:231], s[30:31], 0, v[132:133]
	s_mov_b32 m0, s64
	s_nop 0
	global_load_lds_dwordx4 v[230:231], off
	s_waitcnt vmcnt(8)
	s_waitcnt lgkmcnt(0)
	s_barrier
	s_setprio 1
	s_waitcnt lgkmcnt(0)
	v_mfma_f32_16x16x32_bf16 v[126:129], v[154:157], v[186:189], v[126:129]
	v_mfma_f32_16x16x32_bf16 v[122:125], v[162:165], v[186:189], v[122:125]
	v_mfma_f32_16x16x32_bf16 v[118:121], v[154:157], v[194:197], v[118:121]
	v_mfma_f32_16x16x32_bf16 v[114:117], v[162:165], v[194:197], v[114:117]
	v_mfma_f32_16x16x32_bf16 v[94:97], v[154:157], v[202:205], v[94:97]
	v_mfma_f32_16x16x32_bf16 v[90:93], v[162:165], v[202:205], v[90:93]
	v_mfma_f32_16x16x32_bf16 v[78:81], v[154:157], v[210:213], v[78:81]
	v_mfma_f32_16x16x32_bf16 v[74:77], v[162:165], v[210:213], v[74:77]
	v_mfma_f32_16x16x32_bf16 v[126:129], v[158:161], v[190:193], v[126:129]
	v_mfma_f32_16x16x32_bf16 v[122:125], v[166:169], v[190:193], v[122:125]
	v_mfma_f32_16x16x32_bf16 v[118:121], v[158:161], v[198:201], v[118:121]
	v_mfma_f32_16x16x32_bf16 v[114:117], v[166:169], v[198:201], v[114:117]
	v_mfma_f32_16x16x32_bf16 v[94:97], v[158:161], v[206:209], v[94:97]
	v_mfma_f32_16x16x32_bf16 v[90:93], v[166:169], v[206:209], v[90:93]
	v_mfma_f32_16x16x32_bf16 v[78:81], v[158:161], v[218:221], v[78:81]
	v_mfma_f32_16x16x32_bf16 v[74:77], v[166:169], v[218:221], v[74:77]
	s_setprio 0
	s_setprio 1
	v_mfma_f32_16x16x32_bf16 v[110:113], v[170:173], v[186:189], v[110:113]
	v_mfma_f32_16x16x32_bf16 v[106:109], v[178:181], v[186:189], v[106:109]
	v_mfma_f32_16x16x32_bf16 v[102:105], v[170:173], v[194:197], v[102:105]
	v_mfma_f32_16x16x32_bf16 v[98:101], v[178:181], v[194:197], v[98:101]
	v_mfma_f32_16x16x32_bf16 v[86:89], v[170:173], v[202:205], v[86:89]
	v_mfma_f32_16x16x32_bf16 v[82:85], v[178:181], v[202:205], v[82:85]
	v_mfma_f32_16x16x32_bf16 v[70:73], v[170:173], v[210:213], v[70:73]
	v_mfma_f32_16x16x32_bf16 v[66:69], v[178:181], v[210:213], v[66:69]
	v_mfma_f32_16x16x32_bf16 v[110:113], v[174:177], v[190:193], v[110:113]
	v_mfma_f32_16x16x32_bf16 v[106:109], v[182:185], v[190:193], v[106:109]
	v_mfma_f32_16x16x32_bf16 v[102:105], v[174:177], v[198:201], v[102:105]
	v_mfma_f32_16x16x32_bf16 v[98:101], v[182:185], v[198:201], v[98:101]
	v_mfma_f32_16x16x32_bf16 v[86:89], v[174:177], v[206:209], v[86:89]
	v_mfma_f32_16x16x32_bf16 v[82:85], v[182:185], v[206:209], v[82:85]
	v_mfma_f32_16x16x32_bf16 v[70:73], v[174:177], v[218:221], v[70:73]
	v_mfma_f32_16x16x32_bf16 v[66:69], v[182:185], v[218:221], v[66:69]
	s_setprio 0
	s_barrier
	s_add_i32 s30, s80, s37
	v_lshl_add_u64 v[222:223], v[222:223], 0, s[16:17]
	s_mov_b32 m0, s30
	ds_read_b128 v[186:189], v152 offset:49152
	ds_read_b128 v[190:193], v152 offset:50176
	ds_read_b128 v[194:197], v152 offset:51200
	ds_read_b128 v[198:201], v152 offset:52224
	ds_read_b128 v[202:205], v152 offset:53248
	ds_read_b128 v[206:209], v152 offset:54272
	ds_read_b128 v[210:213], v152 offset:55296
	ds_read_b128 v[218:221], v152 offset:56320
	global_load_lds_dwordx4 v[222:223], off
	s_add_i32 m0, s30, 0x2000
	s_add_u32 s28, s28, 0x40080
	v_lshl_add_u64 v[222:223], v[224:225], 0, s[16:17]
	s_addc_u32 s29, s29, 0
	s_add_i32 s30, s81, s37
	global_load_lds_dwordx4 v[222:223], off
	v_lshl_add_u64 v[222:223], s[28:29], 0, v[134:135]
	s_mov_b32 m0, s30
	s_nop 0
	global_load_lds_dwordx4 v[222:223], off
	v_lshl_add_u64 v[222:223], s[28:29], 0, v[130:131]
	s_add_i32 m0, s30, 0x2000
	s_nop 0
	global_load_lds_dwordx4 v[222:223], off
	v_lshl_add_u64 v[222:223], v[226:227], 0, s[16:17]
	s_mov_b32 m0, s72
	s_nop 0
	global_load_lds_dwordx4 v[222:223], off
	v_lshl_add_u64 v[222:223], v[228:229], 0, s[16:17]
	s_mov_b32 m0, s73
	s_nop 0
	global_load_lds_dwordx4 v[222:223], off
	s_waitcnt vmcnt(8)
	s_waitcnt lgkmcnt(0)
	s_barrier
	s_setprio 1
	s_waitcnt lgkmcnt(0)
	v_mfma_f32_16x16x32_bf16 v[62:65], v[154:157], v[186:189], v[62:65]
	v_mfma_f32_16x16x32_bf16 v[58:61], v[162:165], v[186:189], v[58:61]
	v_mfma_f32_16x16x32_bf16 v[50:53], v[154:157], v[194:197], v[50:53]
	v_mfma_f32_16x16x32_bf16 v[42:45], v[162:165], v[194:197], v[42:45]
	v_mfma_f32_16x16x32_bf16 v[30:33], v[154:157], v[202:205], v[30:33]
	v_mfma_f32_16x16x32_bf16 v[26:29], v[162:165], v[202:205], v[26:29]
	v_mfma_f32_16x16x32_bf16 v[22:25], v[154:157], v[210:213], v[22:25]
	v_mfma_f32_16x16x32_bf16 v[18:21], v[162:165], v[210:213], v[18:21]
	v_mfma_f32_16x16x32_bf16 v[62:65], v[158:161], v[190:193], v[62:65]
	v_mfma_f32_16x16x32_bf16 v[58:61], v[166:169], v[190:193], v[58:61]
	v_mfma_f32_16x16x32_bf16 v[50:53], v[158:161], v[198:201], v[50:53]
	v_mfma_f32_16x16x32_bf16 v[42:45], v[166:169], v[198:201], v[42:45]
	v_mfma_f32_16x16x32_bf16 v[30:33], v[158:161], v[206:209], v[30:33]
	v_mfma_f32_16x16x32_bf16 v[26:29], v[166:169], v[206:209], v[26:29]
	v_mfma_f32_16x16x32_bf16 v[22:25], v[158:161], v[218:221], v[22:25]
	v_mfma_f32_16x16x32_bf16 v[18:21], v[166:169], v[218:221], v[18:21]
	s_setprio 0
	s_setprio 1
	v_mfma_f32_16x16x32_bf16 v[54:57], v[170:173], v[186:189], v[54:57]
	v_mfma_f32_16x16x32_bf16 v[46:49], v[178:181], v[186:189], v[46:49]
	v_mfma_f32_16x16x32_bf16 v[38:41], v[170:173], v[194:197], v[38:41]
	v_mfma_f32_16x16x32_bf16 v[34:37], v[178:181], v[194:197], v[34:37]
	v_mfma_f32_16x16x32_bf16 v[14:17], v[170:173], v[202:205], v[14:17]
	v_mfma_f32_16x16x32_bf16 v[10:13], v[178:181], v[202:205], v[10:13]
	v_mfma_f32_16x16x32_bf16 v[6:9], v[170:173], v[210:213], v[6:9]
	v_mfma_f32_16x16x32_bf16 v[2:5], v[178:181], v[210:213], v[2:5]
	v_mfma_f32_16x16x32_bf16 v[54:57], v[174:177], v[190:193], v[54:57]
	v_mfma_f32_16x16x32_bf16 v[46:49], v[182:185], v[190:193], v[46:49]
	v_mfma_f32_16x16x32_bf16 v[38:41], v[174:177], v[198:201], v[38:41]
	v_mfma_f32_16x16x32_bf16 v[34:37], v[182:185], v[198:201], v[34:37]
	v_mfma_f32_16x16x32_bf16 v[14:17], v[174:177], v[206:209], v[14:17]
	v_mfma_f32_16x16x32_bf16 v[10:13], v[182:185], v[206:209], v[10:13]
	v_mfma_f32_16x16x32_bf16 v[6:9], v[174:177], v[218:221], v[6:9]
	v_mfma_f32_16x16x32_bf16 v[2:5], v[182:185], v[218:221], v[2:5]
	s_setprio 0
	s_add_i32 s79, s79, 2
	s_add_u32 s26, s26, 0x100
	s_addc_u32 s27, s27, 0
	s_cmp_gt_u32 s79, 13
	s_barrier
	s_cbranch_scc0 .LBB0_451
	s_add_u32 s4, s4, 0xffffff00
	s_addc_u32 s5, s5, -1
	s_andn2_b64 vcc, exec, s[8:9]
	s_cbranch_vccnz .LBB0_446
	v_mov_b32_e32 v2, 0
	s_mov_b32 s2, s18
	s_mov_b32 s86, s20
	s_mov_b64 s[10:11], s[24:25]
	s_mov_b32 s65, s76
	v_mov_b32_e32 v3, v2
	v_mov_b32_e32 v4, v2
	v_mov_b32_e32 v5, v2
	v_mov_b32_e32 v6, v2
	v_mov_b32_e32 v7, v2
	v_mov_b32_e32 v8, v2
	v_mov_b32_e32 v9, v2
	v_mov_b32_e32 v10, v2
	v_mov_b32_e32 v11, v2
	v_mov_b32_e32 v12, v2
	v_mov_b32_e32 v13, v2
	v_mov_b32_e32 v14, v2
	v_mov_b32_e32 v15, v2
	v_mov_b32_e32 v16, v2
	v_mov_b32_e32 v17, v2
	v_mov_b32_e32 v34, v2
	v_mov_b32_e32 v35, v2
	v_mov_b32_e32 v36, v2
	v_mov_b32_e32 v37, v2
	v_mov_b32_e32 v38, v2
	v_mov_b32_e32 v39, v2
	v_mov_b32_e32 v40, v2
	v_mov_b32_e32 v41, v2
	v_mov_b32_e32 v46, v2
	v_mov_b32_e32 v47, v2
	v_mov_b32_e32 v48, v2
	v_mov_b32_e32 v49, v2
	v_mov_b32_e32 v54, v2
	v_mov_b32_e32 v55, v2
	v_mov_b32_e32 v56, v2
	v_mov_b32_e32 v57, v2
	v_mov_b32_e32 v18, v2
	v_mov_b32_e32 v19, v2
	v_mov_b32_e32 v20, v2
	v_mov_b32_e32 v21, v2
	v_mov_b32_e32 v22, v2
	v_mov_b32_e32 v23, v2
	v_mov_b32_e32 v24, v2
	v_mov_b32_e32 v25, v2
	v_mov_b32_e32 v26, v2
	v_mov_b32_e32 v27, v2
	v_mov_b32_e32 v28, v2
	v_mov_b32_e32 v29, v2
	v_mov_b32_e32 v30, v2
	v_mov_b32_e32 v31, v2
	v_mov_b32_e32 v32, v2
	v_mov_b32_e32 v33, v2
	v_mov_b32_e32 v42, v2
	v_mov_b32_e32 v43, v2
	v_mov_b32_e32 v44, v2
	v_mov_b32_e32 v45, v2
	v_mov_b32_e32 v50, v2
	v_mov_b32_e32 v51, v2
	v_mov_b32_e32 v52, v2
	v_mov_b32_e32 v53, v2
	v_mov_b32_e32 v58, v2
	v_mov_b32_e32 v59, v2
	v_mov_b32_e32 v60, v2
	v_mov_b32_e32 v61, v2
	v_mov_b32_e32 v62, v2
	v_mov_b32_e32 v63, v2
	v_mov_b32_e32 v64, v2
	v_mov_b32_e32 v65, v2
	v_mov_b32_e32 v66, v2
	v_mov_b32_e32 v67, v2
	v_mov_b32_e32 v68, v2
	v_mov_b32_e32 v69, v2
	v_mov_b32_e32 v70, v2
	v_mov_b32_e32 v71, v2
	v_mov_b32_e32 v72, v2
	v_mov_b32_e32 v73, v2
	v_mov_b32_e32 v82, v2
	v_mov_b32_e32 v83, v2
	v_mov_b32_e32 v84, v2
	v_mov_b32_e32 v85, v2
	v_mov_b32_e32 v86, v2
	v_mov_b32_e32 v87, v2
	v_mov_b32_e32 v88, v2
	v_mov_b32_e32 v89, v2
	v_mov_b32_e32 v98, v2
	v_mov_b32_e32 v99, v2
	v_mov_b32_e32 v100, v2
	v_mov_b32_e32 v101, v2
	v_mov_b32_e32 v102, v2
	v_mov_b32_e32 v103, v2
	v_mov_b32_e32 v104, v2
	v_mov_b32_e32 v105, v2
	v_mov_b32_e32 v106, v2
	v_mov_b32_e32 v107, v2
	v_mov_b32_e32 v108, v2
	v_mov_b32_e32 v109, v2
	v_mov_b32_e32 v110, v2
	v_mov_b32_e32 v111, v2
	v_mov_b32_e32 v112, v2
	v_mov_b32_e32 v113, v2
	v_mov_b32_e32 v74, v2
	v_mov_b32_e32 v75, v2
	v_mov_b32_e32 v76, v2
	v_mov_b32_e32 v77, v2
	v_mov_b32_e32 v78, v2
	v_mov_b32_e32 v79, v2
	v_mov_b32_e32 v80, v2
	v_mov_b32_e32 v81, v2
	v_mov_b32_e32 v90, v2
	v_mov_b32_e32 v91, v2
	v_mov_b32_e32 v92, v2
	v_mov_b32_e32 v93, v2
	v_mov_b32_e32 v94, v2
	v_mov_b32_e32 v95, v2
	v_mov_b32_e32 v96, v2
	v_mov_b32_e32 v97, v2
	v_mov_b32_e32 v114, v2
	v_mov_b32_e32 v115, v2
	v_mov_b32_e32 v116, v2
	v_mov_b32_e32 v117, v2
	v_mov_b32_e32 v118, v2
	v_mov_b32_e32 v119, v2
	v_mov_b32_e32 v120, v2
	v_mov_b32_e32 v121, v2
	v_mov_b32_e32 v122, v2
	v_mov_b32_e32 v123, v2
	v_mov_b32_e32 v124, v2
	v_mov_b32_e32 v125, v2
	v_mov_b32_e32 v126, v2
	v_mov_b32_e32 v127, v2
	v_mov_b32_e32 v128, v2
	v_mov_b32_e32 v129, v2
	s_andn2_b64 vcc, exec, s[6:7]
	s_cbranch_vccnz .LBB0_447

.LBB0_581:
	ds_read_b128 v[130:133], v168
	ds_read_b128 v[134:137], v168 offset:1024
	ds_read_b128 v[138:141], v168 offset:2048
	ds_read_b128 v[142:145], v168 offset:3072
	ds_read_b128 v[162:165], v169
	ds_read_b128 v[172:175], v169 offset:1024
	ds_read_b128 v[176:179], v169 offset:2048
	ds_read_b128 v[180:183], v169 offset:3072
	s_add_u32 s56, s44, 0xfffc0080
	s_addc_u32 s57, s45, -1
	s_cmp_eq_u32 s80, 12
	s_cselect_b32 s59, s4, s57
	s_cselect_b32 s58, s5, s56
	s_cselect_b32 s57, s29, s79
	s_cselect_b32 s56, s31, s78
	v_lshl_add_u64 v[216:217], s[44:45], 0, v[154:155]
	s_add_i32 m0, s41, 0xc000
	ds_read_b128 v[184:187], v170
	ds_read_b128 v[188:191], v170 offset:1024
	ds_read_b128 v[192:195], v170 offset:2048
	ds_read_b128 v[196:199], v170 offset:3072
	ds_read_b128 v[200:203], v170 offset:4096
	ds_read_b128 v[204:207], v170 offset:5120
	ds_read_b128 v[208:211], v170 offset:6144
	ds_read_b128 v[212:215], v170 offset:7168
	global_load_lds_dwordx4 v[216:217], off
	v_lshl_add_u64 v[216:217], s[44:45], 0, v[156:157]
	s_add_i32 m0, s41, 0xe000
	s_nop 0
	global_load_lds_dwordx4 v[216:217], off
	s_waitcnt vmcnt(8)
	s_waitcnt lgkmcnt(0)
	s_barrier
	s_setprio 1
	s_waitcnt lgkmcnt(0)
	v_mfma_f32_16x16x32_bf16 v[126:129], v[130:133], v[184:187], v[126:129]
	v_mfma_f32_16x16x32_bf16 v[122:125], v[138:141], v[184:187], v[122:125]
	v_mfma_f32_16x16x32_bf16 v[118:121], v[130:133], v[192:195], v[118:121]
	v_mfma_f32_16x16x32_bf16 v[114:117], v[138:141], v[192:195], v[114:117]
	v_mfma_f32_16x16x32_bf16 v[94:97], v[130:133], v[200:203], v[94:97]
	v_mfma_f32_16x16x32_bf16 v[90:93], v[138:141], v[200:203], v[90:93]
	v_mfma_f32_16x16x32_bf16 v[78:81], v[130:133], v[208:211], v[78:81]
	v_mfma_f32_16x16x32_bf16 v[74:77], v[138:141], v[208:211], v[74:77]
	v_mfma_f32_16x16x32_bf16 v[126:129], v[134:137], v[188:191], v[126:129]
	v_mfma_f32_16x16x32_bf16 v[122:125], v[142:145], v[188:191], v[122:125]
	v_mfma_f32_16x16x32_bf16 v[118:121], v[134:137], v[196:199], v[118:121]
	v_mfma_f32_16x16x32_bf16 v[114:117], v[142:145], v[196:199], v[114:117]
	v_mfma_f32_16x16x32_bf16 v[94:97], v[134:137], v[204:207], v[94:97]
	v_mfma_f32_16x16x32_bf16 v[90:93], v[142:145], v[204:207], v[90:93]
	v_mfma_f32_16x16x32_bf16 v[78:81], v[134:137], v[212:215], v[78:81]
	v_mfma_f32_16x16x32_bf16 v[74:77], v[142:145], v[212:215], v[74:77]
	s_setprio 0
	s_setprio 1
	v_mfma_f32_16x16x32_bf16 v[110:113], v[162:165], v[184:187], v[110:113]
	v_mfma_f32_16x16x32_bf16 v[106:109], v[176:179], v[184:187], v[106:109]
	v_mfma_f32_16x16x32_bf16 v[102:105], v[162:165], v[192:195], v[102:105]
	v_mfma_f32_16x16x32_bf16 v[98:101], v[176:179], v[192:195], v[98:101]
	v_mfma_f32_16x16x32_bf16 v[86:89], v[162:165], v[200:203], v[86:89]
	v_mfma_f32_16x16x32_bf16 v[82:85], v[176:179], v[200:203], v[82:85]
	v_mfma_f32_16x16x32_bf16 v[70:73], v[162:165], v[208:211], v[70:73]
	v_mfma_f32_16x16x32_bf16 v[66:69], v[176:179], v[208:211], v[66:69]
	v_mfma_f32_16x16x32_bf16 v[110:113], v[172:175], v[188:191], v[110:113]
	v_mfma_f32_16x16x32_bf16 v[106:109], v[180:183], v[188:191], v[106:109]
	v_mfma_f32_16x16x32_bf16 v[102:105], v[172:175], v[196:199], v[102:105]
	v_mfma_f32_16x16x32_bf16 v[98:101], v[180:183], v[196:199], v[98:101]
	v_mfma_f32_16x16x32_bf16 v[86:89], v[172:175], v[204:207], v[86:89]
	v_mfma_f32_16x16x32_bf16 v[82:85], v[180:183], v[204:207], v[82:85]
	v_mfma_f32_16x16x32_bf16 v[70:73], v[172:175], v[212:215], v[70:73]
	v_mfma_f32_16x16x32_bf16 v[66:69], v[180:183], v[212:215], v[66:69]
	s_setprio 0
	s_barrier
	s_add_i32 s81, s71, s3
	v_lshl_add_u64 v[216:217], s[56:57], 0, v[150:151]
	s_mov_b32 m0, s81
	ds_read_b128 v[184:187], v170 offset:16384
	ds_read_b128 v[188:191], v170 offset:17408
	ds_read_b128 v[192:195], v170 offset:18432
	ds_read_b128 v[196:199], v170 offset:19456
	ds_read_b128 v[200:203], v170 offset:20480
	ds_read_b128 v[204:207], v170 offset:21504
	ds_read_b128 v[208:211], v170 offset:22528
	ds_read_b128 v[212:215], v170 offset:23552
	global_load_lds_dwordx4 v[216:217], off
	s_add_i32 m0, s81, 0x2000
	s_add_u32 s82, s56, 0x40000
	v_lshl_add_u64 v[218:219], s[56:57], 0, v[146:147]
	s_addc_u32 s83, s57, 0
	s_add_i32 s81, s72, s3
	global_load_lds_dwordx4 v[218:219], off
	v_lshl_add_u64 v[220:221], s[82:83], 0, v[150:151]
	s_mov_b32 m0, s81
	v_lshl_add_u64 v[222:223], s[58:59], 0, v[148:149]
	global_load_lds_dwordx4 v[220:221], off
	v_lshl_add_u64 v[220:221], s[82:83], 0, v[146:147]
	s_add_i32 m0, s81, 0x2000
	s_nop 0
	global_load_lds_dwordx4 v[220:221], off
	v_lshl_add_u64 v[220:221], s[58:59], 0, v[152:153]
	s_mov_b32 m0, s41
	s_nop 0
	global_load_lds_dwordx4 v[220:221], off
	s_mov_b32 m0, s60
	s_nop 0
	global_load_lds_dwordx4 v[222:223], off
	s_waitcnt vmcnt(8)
	s_waitcnt lgkmcnt(0)
	s_barrier
	s_setprio 1
	s_waitcnt lgkmcnt(0)
	v_mfma_f32_16x16x32_bf16 v[62:65], v[130:133], v[184:187], v[62:65]
	v_mfma_f32_16x16x32_bf16 v[58:61], v[138:141], v[184:187], v[58:61]
	v_mfma_f32_16x16x32_bf16 v[46:49], v[130:133], v[192:195], v[46:49]
	v_mfma_f32_16x16x32_bf16 v[42:45], v[138:141], v[192:195], v[42:45]
	v_mfma_f32_16x16x32_bf16 v[30:33], v[130:133], v[200:203], v[30:33]
	v_mfma_f32_16x16x32_bf16 v[26:29], v[138:141], v[200:203], v[26:29]
	v_mfma_f32_16x16x32_bf16 v[14:17], v[130:133], v[208:211], v[14:17]
	v_mfma_f32_16x16x32_bf16 v[10:13], v[138:141], v[208:211], v[10:13]
	v_mfma_f32_16x16x32_bf16 v[62:65], v[134:137], v[188:191], v[62:65]
	v_mfma_f32_16x16x32_bf16 v[58:61], v[142:145], v[188:191], v[58:61]
	v_mfma_f32_16x16x32_bf16 v[46:49], v[134:137], v[196:199], v[46:49]
	v_mfma_f32_16x16x32_bf16 v[42:45], v[142:145], v[196:199], v[42:45]
	v_mfma_f32_16x16x32_bf16 v[30:33], v[134:137], v[204:207], v[30:33]
	v_mfma_f32_16x16x32_bf16 v[26:29], v[142:145], v[204:207], v[26:29]
	v_mfma_f32_16x16x32_bf16 v[14:17], v[134:137], v[212:215], v[14:17]
	v_mfma_f32_16x16x32_bf16 v[10:13], v[142:145], v[212:215], v[10:13]
	s_setprio 0
	s_setprio 1
	v_mfma_f32_16x16x32_bf16 v[54:57], v[162:165], v[184:187], v[54:57]
	v_mfma_f32_16x16x32_bf16 v[50:53], v[176:179], v[184:187], v[50:53]
	v_mfma_f32_16x16x32_bf16 v[38:41], v[162:165], v[192:195], v[38:41]
	v_mfma_f32_16x16x32_bf16 v[34:37], v[176:179], v[192:195], v[34:37]
	v_mfma_f32_16x16x32_bf16 v[22:25], v[162:165], v[200:203], v[22:25]
	v_mfma_f32_16x16x32_bf16 v[18:21], v[176:179], v[200:203], v[18:21]
	v_mfma_f32_16x16x32_bf16 v[6:9], v[162:165], v[208:211], v[6:9]
	v_mfma_f32_16x16x32_bf16 v[2:5], v[176:179], v[208:211], v[2:5]
	v_mfma_f32_16x16x32_bf16 v[54:57], v[172:175], v[188:191], v[54:57]
	v_mfma_f32_16x16x32_bf16 v[50:53], v[180:183], v[188:191], v[50:53]
	v_mfma_f32_16x16x32_bf16 v[38:41], v[172:175], v[196:199], v[38:41]
	v_mfma_f32_16x16x32_bf16 v[34:37], v[180:183], v[196:199], v[34:37]
	v_mfma_f32_16x16x32_bf16 v[22:25], v[172:175], v[204:207], v[22:25]
	v_mfma_f32_16x16x32_bf16 v[18:21], v[180:183], v[204:207], v[18:21]
	v_mfma_f32_16x16x32_bf16 v[6:9], v[172:175], v[212:215], v[6:9]
	v_mfma_f32_16x16x32_bf16 v[2:5], v[180:183], v[212:215], v[2:5]
	s_setprio 0
	s_barrier
	s_add_i32 s81, 0, 0x18000
	s_add_i32 s82, 0, 0x1c000
	v_add_u32_e32 v142, s81, v166
	v_add_u32_e32 v171, s82, v166
	ds_read_b128 v[130:133], v142
	ds_read_b128 v[134:137], v142 offset:1024
	ds_read_b128 v[138:141], v142 offset:2048
	ds_read_b128 v[142:145], v142 offset:3072
	ds_read_b128 v[162:165], v171
	ds_read_b128 v[172:175], v171 offset:1024
	ds_read_b128 v[176:179], v171 offset:2048
	ds_read_b128 v[180:183], v171 offset:3072
	s_add_u32 s58, s58, 0x40000
	s_addc_u32 s59, s59, 0
	s_mov_b32 m0, s61
	v_lshl_add_u64 v[224:225], s[58:59], 0, v[152:153]
	ds_read_b128 v[184:187], v170 offset:32768
	ds_read_b128 v[188:191], v170 offset:33792
	ds_read_b128 v[192:195], v170 offset:34816
	ds_read_b128 v[196:199], v170 offset:35840
	ds_read_b128 v[200:203], v170 offset:36864
	ds_read_b128 v[204:207], v170 offset:37888
	ds_read_b128 v[208:211], v170 offset:38912
	ds_read_b128 v[212:215], v170 offset:39936
	global_load_lds_dwordx4 v[224:225], off
	v_lshl_add_u64 v[224:225], s[58:59], 0, v[148:149]
	s_mov_b32 m0, s62
	s_nop 0
	global_load_lds_dwordx4 v[224:225], off
	s_waitcnt vmcnt(8)
	s_waitcnt lgkmcnt(0)
	s_barrier
	s_setprio 1
	s_waitcnt lgkmcnt(0)
	v_mfma_f32_16x16x32_bf16 v[126:129], v[130:133], v[184:187], v[126:129]
	v_mfma_f32_16x16x32_bf16 v[122:125], v[138:141], v[184:187], v[122:125]
	v_mfma_f32_16x16x32_bf16 v[118:121], v[130:133], v[192:195], v[118:121]
	v_mfma_f32_16x16x32_bf16 v[114:117], v[138:141], v[192:195], v[114:117]
	v_mfma_f32_16x16x32_bf16 v[94:97], v[130:133], v[200:203], v[94:97]
	v_mfma_f32_16x16x32_bf16 v[90:93], v[138:141], v[200:203], v[90:93]
	v_mfma_f32_16x16x32_bf16 v[78:81], v[130:133], v[208:211], v[78:81]
	v_mfma_f32_16x16x32_bf16 v[74:77], v[138:141], v[208:211], v[74:77]
	v_mfma_f32_16x16x32_bf16 v[126:129], v[134:137], v[188:191], v[126:129]
	v_mfma_f32_16x16x32_bf16 v[122:125], v[142:145], v[188:191], v[122:125]
	v_mfma_f32_16x16x32_bf16 v[118:121], v[134:137], v[196:199], v[118:121]
	v_mfma_f32_16x16x32_bf16 v[114:117], v[142:145], v[196:199], v[114:117]
	v_mfma_f32_16x16x32_bf16 v[94:97], v[134:137], v[204:207], v[94:97]
	v_mfma_f32_16x16x32_bf16 v[90:93], v[142:145], v[204:207], v[90:93]
	v_mfma_f32_16x16x32_bf16 v[78:81], v[134:137], v[212:215], v[78:81]
	v_mfma_f32_16x16x32_bf16 v[74:77], v[142:145], v[212:215], v[74:77]
	s_setprio 0
	s_setprio 1
	v_mfma_f32_16x16x32_bf16 v[110:113], v[162:165], v[184:187], v[110:113]
	v_mfma_f32_16x16x32_bf16 v[106:109], v[176:179], v[184:187], v[106:109]
	v_mfma_f32_16x16x32_bf16 v[102:105], v[162:165], v[192:195], v[102:105]
	v_mfma_f32_16x16x32_bf16 v[98:101], v[176:179], v[192:195], v[98:101]
	v_mfma_f32_16x16x32_bf16 v[86:89], v[162:165], v[200:203], v[86:89]
	v_mfma_f32_16x16x32_bf16 v[82:85], v[176:179], v[200:203], v[82:85]
	v_mfma_f32_16x16x32_bf16 v[70:73], v[162:165], v[208:211], v[70:73]
	v_mfma_f32_16x16x32_bf16 v[66:69], v[176:179], v[208:211], v[66:69]
	v_mfma_f32_16x16x32_bf16 v[110:113], v[172:175], v[188:191], v[110:113]
	v_mfma_f32_16x16x32_bf16 v[106:109], v[180:183], v[188:191], v[106:109]
	v_mfma_f32_16x16x32_bf16 v[102:105], v[172:175], v[196:199], v[102:105]
	v_mfma_f32_16x16x32_bf16 v[98:101], v[180:183], v[196:199], v[98:101]
	v_mfma_f32_16x16x32_bf16 v[86:89], v[172:175], v[204:207], v[86:89]
	v_mfma_f32_16x16x32_bf16 v[82:85], v[180:183], v[204:207], v[82:85]
	v_mfma_f32_16x16x32_bf16 v[70:73], v[172:175], v[212:215], v[70:73]
	v_mfma_f32_16x16x32_bf16 v[66:69], v[180:183], v[212:215], v[66:69]
	s_setprio 0
	s_barrier
	s_add_i32 s58, s81, s3
	v_lshl_add_u64 v[216:217], v[216:217], 0, s[16:17]
	s_mov_b32 m0, s58
	ds_read_b128 v[184:187], v170 offset:49152
	ds_read_b128 v[188:191], v170 offset:50176
	ds_read_b128 v[192:195], v170 offset:51200
	ds_read_b128 v[196:199], v170 offset:52224
	ds_read_b128 v[200:203], v170 offset:53248
	ds_read_b128 v[204:207], v170 offset:54272
	ds_read_b128 v[208:211], v170 offset:55296
	ds_read_b128 v[212:215], v170 offset:56320
	global_load_lds_dwordx4 v[216:217], off
	s_add_i32 m0, s58, 0x2000
	s_add_u32 s56, s56, 0x40080
	v_lshl_add_u64 v[216:217], v[218:219], 0, s[16:17]
	s_addc_u32 s57, s57, 0
	s_add_i32 s58, s82, s3
	global_load_lds_dwordx4 v[216:217], off
	v_lshl_add_u64 v[216:217], s[56:57], 0, v[150:151]
	s_mov_b32 m0, s58
	s_nop 0
	global_load_lds_dwordx4 v[216:217], off
	v_lshl_add_u64 v[216:217], s[56:57], 0, v[146:147]
	s_add_i32 m0, s58, 0x2000
	s_nop 0
	global_load_lds_dwordx4 v[216:217], off
	v_lshl_add_u64 v[216:217], v[220:221], 0, s[16:17]
	s_mov_b32 m0, s64
	s_nop 0
	global_load_lds_dwordx4 v[216:217], off
	v_lshl_add_u64 v[216:217], v[222:223], 0, s[16:17]
	s_mov_b32 m0, s65
	s_nop 0
	global_load_lds_dwordx4 v[216:217], off
	s_waitcnt vmcnt(8)
	s_waitcnt lgkmcnt(0)
	s_barrier
	s_setprio 1
	s_waitcnt lgkmcnt(0)
	v_mfma_f32_16x16x32_bf16 v[62:65], v[130:133], v[184:187], v[62:65]
	v_mfma_f32_16x16x32_bf16 v[58:61], v[138:141], v[184:187], v[58:61]
	v_mfma_f32_16x16x32_bf16 v[46:49], v[130:133], v[192:195], v[46:49]
	v_mfma_f32_16x16x32_bf16 v[42:45], v[138:141], v[192:195], v[42:45]
	v_mfma_f32_16x16x32_bf16 v[30:33], v[130:133], v[200:203], v[30:33]
	v_mfma_f32_16x16x32_bf16 v[26:29], v[138:141], v[200:203], v[26:29]
	v_mfma_f32_16x16x32_bf16 v[14:17], v[130:133], v[208:211], v[14:17]
	v_mfma_f32_16x16x32_bf16 v[10:13], v[138:141], v[208:211], v[10:13]
	v_mfma_f32_16x16x32_bf16 v[62:65], v[134:137], v[188:191], v[62:65]
	v_mfma_f32_16x16x32_bf16 v[58:61], v[142:145], v[188:191], v[58:61]
	v_mfma_f32_16x16x32_bf16 v[46:49], v[134:137], v[196:199], v[46:49]
	v_mfma_f32_16x16x32_bf16 v[42:45], v[142:145], v[196:199], v[42:45]
	v_mfma_f32_16x16x32_bf16 v[30:33], v[134:137], v[204:207], v[30:33]
	v_mfma_f32_16x16x32_bf16 v[26:29], v[142:145], v[204:207], v[26:29]
	v_mfma_f32_16x16x32_bf16 v[14:17], v[134:137], v[212:215], v[14:17]
	v_mfma_f32_16x16x32_bf16 v[10:13], v[142:145], v[212:215], v[10:13]
	s_setprio 0
	s_setprio 1
	v_mfma_f32_16x16x32_bf16 v[54:57], v[162:165], v[184:187], v[54:57]
	v_mfma_f32_16x16x32_bf16 v[50:53], v[176:179], v[184:187], v[50:53]
	v_mfma_f32_16x16x32_bf16 v[38:41], v[162:165], v[192:195], v[38:41]
	v_mfma_f32_16x16x32_bf16 v[34:37], v[176:179], v[192:195], v[34:37]
	v_mfma_f32_16x16x32_bf16 v[22:25], v[162:165], v[200:203], v[22:25]
	v_mfma_f32_16x16x32_bf16 v[18:21], v[176:179], v[200:203], v[18:21]
	v_mfma_f32_16x16x32_bf16 v[6:9], v[162:165], v[208:211], v[6:9]
	v_mfma_f32_16x16x32_bf16 v[2:5], v[176:179], v[208:211], v[2:5]
	v_mfma_f32_16x16x32_bf16 v[54:57], v[172:175], v[188:191], v[54:57]
	v_mfma_f32_16x16x32_bf16 v[50:53], v[180:183], v[188:191], v[50:53]
	v_mfma_f32_16x16x32_bf16 v[38:41], v[172:175], v[196:199], v[38:41]
	v_mfma_f32_16x16x32_bf16 v[34:37], v[180:183], v[196:199], v[34:37]
	v_mfma_f32_16x16x32_bf16 v[22:25], v[172:175], v[204:207], v[22:25]
	v_mfma_f32_16x16x32_bf16 v[18:21], v[180:183], v[204:207], v[18:21]
	v_mfma_f32_16x16x32_bf16 v[6:9], v[172:175], v[212:215], v[6:9]
	v_mfma_f32_16x16x32_bf16 v[2:5], v[180:183], v[212:215], v[2:5]
	s_setprio 0
	s_add_i32 s80, s80, 2
	s_add_u32 s44, s44, 0x100
	s_addc_u32 s45, s45, 0
	s_add_u32 s78, s78, 0x100
	s_addc_u32 s79, s79, 0
	s_cmp_gt_u32 s80, 13
	s_barrier
	s_cbranch_scc0 .LBB0_581
	s_and_b64 vcc, exec, s[18:19]
	s_cbranch_vccz .LBB0_584
	s_barrier

.LBB0_649:
	v_add_u32_e32 v164, s57, v150
	v_add_u32_e32 v173, s58, v150
	s_add_u32 s28, s14, s26
	ds_read_b128 v[152:155], v164
	ds_read_b128 v[156:159], v164 offset:1024
	ds_read_b128 v[160:163], v164 offset:2048
	ds_read_b128 v[164:167], v164 offset:3072
	ds_read_b128 v[168:171], v173
	ds_read_b128 v[174:177], v173 offset:1024
	ds_read_b128 v[178:181], v173 offset:2048
	ds_read_b128 v[182:185], v173 offset:3072
	s_addc_u32 s29, s15, s27
	s_add_u32 s28, s28, 0x100
	s_addc_u32 s29, s29, 0
	s_add_u32 s65, s60, s26
	s_addc_u32 s66, s61, s27
	s_cmpk_eq_i32 s26, 0x1f00
	s_cselect_b32 s31, s21, s29
	s_cselect_b32 s30, s62, s28
	s_cselect_b32 s29, s19, s66
	s_cselect_b32 s28, s63, s65
	v_lshl_add_u64 v[218:219], v[146:147], 0, s[26:27]
	s_add_i32 m0, s37, 0xc000
	ds_read_b128 v[186:189], v151
	ds_read_b128 v[190:193], v151 offset:1024
	ds_read_b128 v[194:197], v151 offset:2048
	ds_read_b128 v[198:201], v151 offset:3072
	ds_read_b128 v[202:205], v151 offset:4096
	ds_read_b128 v[206:209], v151 offset:5120
	global_load_lds_dwordx4 v[218:219], off
	v_lshl_add_u64 v[218:219], v[148:149], 0, s[26:27]
	s_add_i32 m0, s37, 0xe000
	s_nop 0
	global_load_lds_dwordx4 v[218:219], off
	s_waitcnt vmcnt(8)
	s_waitcnt lgkmcnt(0)
	s_barrier
	s_setprio 1
	s_waitcnt lgkmcnt(0)
	v_mfma_f32_16x16x32_bf16 v[114:117], v[152:155], v[186:189], v[114:117]
	v_mfma_f32_16x16x32_bf16 v[106:109], v[160:163], v[186:189], v[106:109]
	v_mfma_f32_16x16x32_bf16 v[130:133], v[152:155], v[194:197], v[130:133]
	v_mfma_f32_16x16x32_bf16 v[78:81], v[160:163], v[194:197], v[78:81]
	v_mfma_f32_16x16x32_bf16 v[126:129], v[152:155], v[202:205], v[126:129]
	v_mfma_f32_16x16x32_bf16 v[118:121], v[160:163], v[202:205], v[118:121]
	v_mfma_f32_16x16x32_bf16 v[114:117], v[156:159], v[190:193], v[114:117]
	v_mfma_f32_16x16x32_bf16 v[106:109], v[164:167], v[190:193], v[106:109]
	v_mfma_f32_16x16x32_bf16 v[130:133], v[156:159], v[198:201], v[130:133]
	v_mfma_f32_16x16x32_bf16 v[78:81], v[164:167], v[198:201], v[78:81]
	v_mfma_f32_16x16x32_bf16 v[126:129], v[156:159], v[206:209], v[126:129]
	v_mfma_f32_16x16x32_bf16 v[118:121], v[164:167], v[206:209], v[118:121]
	s_setprio 0
	s_setprio 1
	v_mfma_f32_16x16x32_bf16 v[98:101], v[168:171], v[186:189], v[98:101]
	v_mfma_f32_16x16x32_bf16 v[82:85], v[178:181], v[186:189], v[82:85]
	v_mfma_f32_16x16x32_bf16 v[86:89], v[168:171], v[194:197], v[86:89]
	v_mfma_f32_16x16x32_bf16 v[90:93], v[178:181], v[194:197], v[90:93]
	v_mfma_f32_16x16x32_bf16 v[110:113], v[168:171], v[202:205], v[110:113]
	v_mfma_f32_16x16x32_bf16 v[94:97], v[178:181], v[202:205], v[94:97]
	v_mfma_f32_16x16x32_bf16 v[98:101], v[174:177], v[190:193], v[98:101]
	v_mfma_f32_16x16x32_bf16 v[82:85], v[182:185], v[190:193], v[82:85]
	v_mfma_f32_16x16x32_bf16 v[86:89], v[174:177], v[198:201], v[86:89]
	v_mfma_f32_16x16x32_bf16 v[90:93], v[182:185], v[198:201], v[90:93]
	v_mfma_f32_16x16x32_bf16 v[110:113], v[174:177], v[206:209], v[110:113]
	v_mfma_f32_16x16x32_bf16 v[94:97], v[182:185], v[206:209], v[94:97]
	s_setprio 0
	s_barrier
	s_add_i32 s65, s57, s35
	v_lshl_add_u64 v[218:219], s[28:29], 0, v[134:135]
	s_mov_b32 m0, s65
	ds_read_b128 v[186:189], v151 offset:16384
	ds_read_b128 v[190:193], v151 offset:17408
	ds_read_b128 v[194:197], v151 offset:18432
	ds_read_b128 v[198:201], v151 offset:19456
	ds_read_b128 v[202:205], v151 offset:20480
	ds_read_b128 v[206:209], v151 offset:21504
	global_load_lds_dwordx4 v[218:219], off
	s_add_i32 m0, s65, 0x2000
	s_add_u32 s66, s28, 0x100000
	v_lshl_add_u64 v[220:221], s[28:29], 0, v[122:123]
	s_addc_u32 s67, s29, 0
	s_add_i32 s65, s58, s35
	global_load_lds_dwordx4 v[220:221], off
	v_lshl_add_u64 v[222:223], s[66:67], 0, v[134:135]
	s_mov_b32 m0, s65
	v_lshl_add_u64 v[224:225], s[30:31], 0, v[124:125]
	global_load_lds_dwordx4 v[222:223], off
	v_lshl_add_u64 v[222:223], s[66:67], 0, v[122:123]
	s_add_i32 m0, s65, 0x2000
	s_nop 0
	global_load_lds_dwordx4 v[222:223], off
	v_lshl_add_u64 v[222:223], s[30:31], 0, v[136:137]
	s_mov_b32 m0, s37
	s_nop 0
	global_load_lds_dwordx4 v[222:223], off
	s_mov_b32 m0, s41
	s_nop 0
	global_load_lds_dwordx4 v[224:225], off
	s_waitcnt vmcnt(8)
	s_waitcnt lgkmcnt(0)
	s_barrier
	s_setprio 1
	s_waitcnt lgkmcnt(0)
	v_mfma_f32_16x16x32_bf16 v[62:65], v[152:155], v[186:189], v[62:65]
	v_mfma_f32_16x16x32_bf16 v[58:61], v[160:163], v[186:189], v[58:61]
	v_mfma_f32_16x16x32_bf16 v[50:53], v[152:155], v[194:197], v[50:53]
	v_mfma_f32_16x16x32_bf16 v[42:45], v[160:163], v[194:197], v[42:45]
	v_mfma_f32_16x16x32_bf16 v[34:37], v[152:155], v[202:205], v[34:37]
	v_mfma_f32_16x16x32_bf16 v[26:29], v[160:163], v[202:205], v[26:29]
	v_mfma_f32_16x16x32_bf16 v[62:65], v[156:159], v[190:193], v[62:65]
	v_mfma_f32_16x16x32_bf16 v[58:61], v[164:167], v[190:193], v[58:61]
	v_mfma_f32_16x16x32_bf16 v[50:53], v[156:159], v[198:201], v[50:53]
	v_mfma_f32_16x16x32_bf16 v[42:45], v[164:167], v[198:201], v[42:45]
	v_mfma_f32_16x16x32_bf16 v[34:37], v[156:159], v[206:209], v[34:37]
	v_mfma_f32_16x16x32_bf16 v[26:29], v[164:167], v[206:209], v[26:29]
	s_setprio 0
	s_setprio 1
	v_mfma_f32_16x16x32_bf16 v[54:57], v[168:171], v[186:189], v[54:57]
	v_mfma_f32_16x16x32_bf16 v[46:49], v[178:181], v[186:189], v[46:49]
	v_mfma_f32_16x16x32_bf16 v[38:41], v[168:171], v[194:197], v[38:41]
	v_mfma_f32_16x16x32_bf16 v[30:33], v[178:181], v[194:197], v[30:33]
	v_mfma_f32_16x16x32_bf16 v[22:25], v[168:171], v[202:205], v[22:25]
	v_mfma_f32_16x16x32_bf16 v[14:17], v[178:181], v[202:205], v[14:17]
	v_mfma_f32_16x16x32_bf16 v[54:57], v[174:177], v[190:193], v[54:57]
	v_mfma_f32_16x16x32_bf16 v[46:49], v[182:185], v[190:193], v[46:49]
	v_mfma_f32_16x16x32_bf16 v[38:41], v[174:177], v[198:201], v[38:41]
	v_mfma_f32_16x16x32_bf16 v[30:33], v[182:185], v[198:201], v[30:33]
	v_mfma_f32_16x16x32_bf16 v[22:25], v[174:177], v[206:209], v[22:25]
	v_mfma_f32_16x16x32_bf16 v[14:17], v[182:185], v[206:209], v[14:17]
	s_setprio 0
	s_barrier
	s_add_i32 s65, 0, 0x18000
	s_add_i32 s66, 0, 0x1c000
	v_add_u32_e32 v164, s65, v150
	v_add_u32_e32 v173, s66, v150
	ds_read_b128 v[152:155], v164
	ds_read_b128 v[156:159], v164 offset:1024
	ds_read_b128 v[160:163], v164 offset:2048
	ds_read_b128 v[164:167], v164 offset:3072
	ds_read_b128 v[168:171], v173
	ds_read_b128 v[174:177], v173 offset:1024
	ds_read_b128 v[178:181], v173 offset:2048
	ds_read_b128 v[182:185], v173 offset:3072
	s_add_u32 s30, s30, 0xc0000
	s_addc_u32 s31, s31, 0
	s_mov_b32 m0, s42
	v_lshl_add_u64 v[226:227], s[30:31], 0, v[136:137]
	ds_read_b128 v[186:189], v151 offset:32768
	ds_read_b128 v[190:193], v151 offset:33792
	ds_read_b128 v[194:197], v151 offset:34816
	ds_read_b128 v[198:201], v151 offset:35840
	ds_read_b128 v[202:205], v151 offset:36864
	ds_read_b128 v[206:209], v151 offset:37888
	global_load_lds_dwordx4 v[226:227], off
	v_lshl_add_u64 v[226:227], s[30:31], 0, v[124:125]
	s_mov_b32 m0, s43
	s_nop 0
	global_load_lds_dwordx4 v[226:227], off
	s_waitcnt vmcnt(8)
	s_waitcnt lgkmcnt(0)
	s_barrier
	s_setprio 1
	s_waitcnt lgkmcnt(0)
	v_mfma_f32_16x16x32_bf16 v[114:117], v[152:155], v[186:189], v[114:117]
	v_mfma_f32_16x16x32_bf16 v[106:109], v[160:163], v[186:189], v[106:109]
	v_mfma_f32_16x16x32_bf16 v[130:133], v[152:155], v[194:197], v[130:133]
	v_mfma_f32_16x16x32_bf16 v[78:81], v[160:163], v[194:197], v[78:81]
	v_mfma_f32_16x16x32_bf16 v[126:129], v[152:155], v[202:205], v[126:129]
	v_mfma_f32_16x16x32_bf16 v[118:121], v[160:163], v[202:205], v[118:121]
	v_mfma_f32_16x16x32_bf16 v[114:117], v[156:159], v[190:193], v[114:117]
	v_mfma_f32_16x16x32_bf16 v[106:109], v[164:167], v[190:193], v[106:109]
	v_mfma_f32_16x16x32_bf16 v[130:133], v[156:159], v[198:201], v[130:133]
	v_mfma_f32_16x16x32_bf16 v[78:81], v[164:167], v[198:201], v[78:81]
	v_mfma_f32_16x16x32_bf16 v[126:129], v[156:159], v[206:209], v[126:129]
	v_mfma_f32_16x16x32_bf16 v[118:121], v[164:167], v[206:209], v[118:121]
	s_setprio 0
	s_setprio 1
	v_mfma_f32_16x16x32_bf16 v[98:101], v[168:171], v[186:189], v[98:101]
	v_mfma_f32_16x16x32_bf16 v[82:85], v[178:181], v[186:189], v[82:85]
	v_mfma_f32_16x16x32_bf16 v[86:89], v[168:171], v[194:197], v[86:89]
	v_mfma_f32_16x16x32_bf16 v[90:93], v[178:181], v[194:197], v[90:93]
	v_mfma_f32_16x16x32_bf16 v[110:113], v[168:171], v[202:205], v[110:113]
	v_mfma_f32_16x16x32_bf16 v[94:97], v[178:181], v[202:205], v[94:97]
	v_mfma_f32_16x16x32_bf16 v[98:101], v[174:177], v[190:193], v[98:101]
	v_mfma_f32_16x16x32_bf16 v[82:85], v[182:185], v[190:193], v[82:85]
	v_mfma_f32_16x16x32_bf16 v[86:89], v[174:177], v[198:201], v[86:89]
	v_mfma_f32_16x16x32_bf16 v[90:93], v[182:185], v[198:201], v[90:93]
	v_mfma_f32_16x16x32_bf16 v[110:113], v[174:177], v[206:209], v[110:113]
	v_mfma_f32_16x16x32_bf16 v[94:97], v[182:185], v[206:209], v[94:97]
	s_setprio 0
	s_barrier
	s_add_i32 s30, s65, s35
	v_lshl_add_u64 v[218:219], v[218:219], 0, s[16:17]
	s_mov_b32 m0, s30
	ds_read_b128 v[186:189], v151 offset:49152
	ds_read_b128 v[190:193], v151 offset:50176
	ds_read_b128 v[194:197], v151 offset:51200
	ds_read_b128 v[198:201], v151 offset:52224
	ds_read_b128 v[202:205], v151 offset:53248
	ds_read_b128 v[206:209], v151 offset:54272
	global_load_lds_dwordx4 v[218:219], off
	s_add_i32 m0, s30, 0x2000
	s_add_u32 s28, s28, 0x100080
	v_lshl_add_u64 v[218:219], v[220:221], 0, s[16:17]
	s_addc_u32 s29, s29, 0
	s_add_i32 s30, s66, s35
	global_load_lds_dwordx4 v[218:219], off
	v_lshl_add_u64 v[218:219], s[28:29], 0, v[134:135]
	s_mov_b32 m0, s30
	s_nop 0
	global_load_lds_dwordx4 v[218:219], off
	v_lshl_add_u64 v[218:219], s[28:29], 0, v[122:123]
	s_add_i32 m0, s30, 0x2000
	s_nop 0
	global_load_lds_dwordx4 v[218:219], off
	v_lshl_add_u64 v[218:219], v[222:223], 0, s[16:17]
	s_mov_b32 m0, s45
	s_nop 0
	global_load_lds_dwordx4 v[218:219], off
	v_lshl_add_u64 v[218:219], v[224:225], 0, s[16:17]
	s_mov_b32 m0, s56
	s_nop 0
	global_load_lds_dwordx4 v[218:219], off
	s_waitcnt vmcnt(8)
	s_waitcnt lgkmcnt(0)
	s_barrier
	s_setprio 1
	s_waitcnt lgkmcnt(0)
	v_mfma_f32_16x16x32_bf16 v[62:65], v[152:155], v[186:189], v[62:65]
	v_mfma_f32_16x16x32_bf16 v[58:61], v[160:163], v[186:189], v[58:61]
	v_mfma_f32_16x16x32_bf16 v[50:53], v[152:155], v[194:197], v[50:53]
	v_mfma_f32_16x16x32_bf16 v[42:45], v[160:163], v[194:197], v[42:45]
	v_mfma_f32_16x16x32_bf16 v[34:37], v[152:155], v[202:205], v[34:37]
	v_mfma_f32_16x16x32_bf16 v[26:29], v[160:163], v[202:205], v[26:29]
	v_mfma_f32_16x16x32_bf16 v[62:65], v[156:159], v[190:193], v[62:65]
	v_mfma_f32_16x16x32_bf16 v[58:61], v[164:167], v[190:193], v[58:61]
	v_mfma_f32_16x16x32_bf16 v[50:53], v[156:159], v[198:201], v[50:53]
	v_mfma_f32_16x16x32_bf16 v[42:45], v[164:167], v[198:201], v[42:45]
	v_mfma_f32_16x16x32_bf16 v[34:37], v[156:159], v[206:209], v[34:37]
	v_mfma_f32_16x16x32_bf16 v[26:29], v[164:167], v[206:209], v[26:29]
	s_setprio 0
	s_setprio 1
	v_mfma_f32_16x16x32_bf16 v[54:57], v[168:171], v[186:189], v[54:57]
	v_mfma_f32_16x16x32_bf16 v[46:49], v[178:181], v[186:189], v[46:49]
	v_mfma_f32_16x16x32_bf16 v[38:41], v[168:171], v[194:197], v[38:41]
	v_mfma_f32_16x16x32_bf16 v[30:33], v[178:181], v[194:197], v[30:33]
	v_mfma_f32_16x16x32_bf16 v[22:25], v[168:171], v[202:205], v[22:25]
	v_mfma_f32_16x16x32_bf16 v[14:17], v[178:181], v[202:205], v[14:17]
	v_mfma_f32_16x16x32_bf16 v[54:57], v[174:177], v[190:193], v[54:57]
	v_mfma_f32_16x16x32_bf16 v[46:49], v[182:185], v[190:193], v[46:49]
	v_mfma_f32_16x16x32_bf16 v[38:41], v[174:177], v[198:201], v[38:41]
	v_mfma_f32_16x16x32_bf16 v[30:33], v[182:185], v[198:201], v[30:33]
	v_mfma_f32_16x16x32_bf16 v[22:25], v[174:177], v[206:209], v[22:25]
	v_mfma_f32_16x16x32_bf16 v[14:17], v[182:185], v[206:209], v[14:17]
	s_setprio 0
	s_add_i32 s64, s64, 2
	s_add_u32 s26, s26, 0x100
	s_addc_u32 s27, s27, 0
	s_cmp_gt_u32 s64, 61
	s_barrier
	s_cbranch_scc0 .LBB0_649
	s_add_u32 s26, s60, 0xffffff00
	s_addc_u32 s27, s61, -1
	s_andn2_b64 vcc, exec, s[4:5]
	s_cbranch_vccnz .LBB0_644
	v_mov_b32_e32 v2, 0
	s_mov_b32 s10, s18
	s_mov_b32 s6, s20
	s_mov_b64 s[14:15], s[24:25]
	s_mov_b32 s44, s59
	v_mov_b32_e32 v3, v2
	v_mov_b32_e32 v4, v2
	v_mov_b32_e32 v5, v2
	v_mov_b32_e32 v6, v2
	v_mov_b32_e32 v7, v2
	v_mov_b32_e32 v8, v2
	v_mov_b32_e32 v9, v2
	v_mov_b32_e32 v14, v2
	v_mov_b32_e32 v15, v2
	v_mov_b32_e32 v16, v2
	v_mov_b32_e32 v17, v2
	v_mov_b32_e32 v22, v2
	v_mov_b32_e32 v23, v2
	v_mov_b32_e32 v24, v2
	v_mov_b32_e32 v25, v2
	v_mov_b32_e32 v30, v2
	v_mov_b32_e32 v31, v2
	v_mov_b32_e32 v32, v2
	v_mov_b32_e32 v33, v2
	v_mov_b32_e32 v38, v2
	v_mov_b32_e32 v39, v2
	v_mov_b32_e32 v40, v2
	v_mov_b32_e32 v41, v2
	v_mov_b32_e32 v46, v2
	v_mov_b32_e32 v47, v2
	v_mov_b32_e32 v48, v2
	v_mov_b32_e32 v49, v2
	v_mov_b32_e32 v54, v2
	v_mov_b32_e32 v55, v2
	v_mov_b32_e32 v56, v2
	v_mov_b32_e32 v57, v2
	v_mov_b32_e32 v10, v2
	v_mov_b32_e32 v11, v2
	v_mov_b32_e32 v12, v2
	v_mov_b32_e32 v13, v2
	v_mov_b32_e32 v18, v2
	v_mov_b32_e32 v19, v2
	v_mov_b32_e32 v20, v2
	v_mov_b32_e32 v21, v2
	v_mov_b32_e32 v26, v2
	v_mov_b32_e32 v27, v2
	v_mov_b32_e32 v28, v2
	v_mov_b32_e32 v29, v2
	v_mov_b32_e32 v34, v2
	v_mov_b32_e32 v35, v2
	v_mov_b32_e32 v36, v2
	v_mov_b32_e32 v37, v2
	v_mov_b32_e32 v42, v2
	v_mov_b32_e32 v43, v2
	v_mov_b32_e32 v44, v2
	v_mov_b32_e32 v45, v2
	v_mov_b32_e32 v50, v2
	v_mov_b32_e32 v51, v2
	v_mov_b32_e32 v52, v2
	v_mov_b32_e32 v53, v2
	v_mov_b32_e32 v58, v2
	v_mov_b32_e32 v59, v2
	v_mov_b32_e32 v60, v2
	v_mov_b32_e32 v61, v2
	v_mov_b32_e32 v62, v2
	v_mov_b32_e32 v63, v2
	v_mov_b32_e32 v64, v2
	v_mov_b32_e32 v65, v2
	v_mov_b32_e32 v66, v2
	v_mov_b32_e32 v67, v2
	v_mov_b32_e32 v68, v2
	v_mov_b32_e32 v69, v2
	v_mov_b32_e32 v70, v2
	v_mov_b32_e32 v71, v2
	v_mov_b32_e32 v72, v2
	v_mov_b32_e32 v73, v2
	v_mov_b32_e32 v94, v2
	v_mov_b32_e32 v95, v2
	v_mov_b32_e32 v96, v2
	v_mov_b32_e32 v97, v2
	v_mov_b32_e32 v110, v2
	v_mov_b32_e32 v111, v2
	v_mov_b32_e32 v112, v2
	v_mov_b32_e32 v113, v2
	v_mov_b32_e32 v90, v2
	v_mov_b32_e32 v91, v2
	v_mov_b32_e32 v92, v2
	v_mov_b32_e32 v93, v2
	v_mov_b32_e32 v86, v2
	v_mov_b32_e32 v87, v2
	v_mov_b32_e32 v88, v2
	v_mov_b32_e32 v89, v2
	v_mov_b32_e32 v82, v2
	v_mov_b32_e32 v83, v2
	v_mov_b32_e32 v84, v2
	v_mov_b32_e32 v85, v2
	v_mov_b32_e32 v98, v2
	v_mov_b32_e32 v99, v2
	v_mov_b32_e32 v100, v2
	v_mov_b32_e32 v101, v2
	v_mov_b32_e32 v74, v2
	v_mov_b32_e32 v75, v2
	v_mov_b32_e32 v76, v2
	v_mov_b32_e32 v77, v2
	v_mov_b32_e32 v102, v2
	v_mov_b32_e32 v103, v2
	v_mov_b32_e32 v104, v2
	v_mov_b32_e32 v105, v2
	v_mov_b32_e32 v118, v2
	v_mov_b32_e32 v119, v2
	v_mov_b32_e32 v120, v2
	v_mov_b32_e32 v121, v2
	v_mov_b32_e32 v126, v2
	v_mov_b32_e32 v127, v2
	v_mov_b32_e32 v128, v2
	v_mov_b32_e32 v129, v2
	v_mov_b32_e32 v78, v2
	v_mov_b32_e32 v79, v2
	v_mov_b32_e32 v80, v2
	v_mov_b32_e32 v81, v2
	v_mov_b32_e32 v130, v2
	v_mov_b32_e32 v131, v2
	v_mov_b32_e32 v132, v2
	v_mov_b32_e32 v133, v2
	v_mov_b32_e32 v106, v2
	v_mov_b32_e32 v107, v2
	v_mov_b32_e32 v108, v2
	v_mov_b32_e32 v109, v2
	v_mov_b32_e32 v114, v2
	v_mov_b32_e32 v115, v2
	v_mov_b32_e32 v116, v2
	v_mov_b32_e32 v117, v2
	s_andn2_b64 vcc, exec, s[0:1]
	s_cbranch_vccnz .LBB0_645
